# GEMM k-loops: post-compute address arithmetic moved into late MFMA slots (after last LDS write) so the half ends at the barrier
# baseline (speedup 1.0000x reference)
; #define G_STORE(ST, S, unused) do { char* d_ = smem + (ST) * STAGE; \
;     *(uint4*)(d_ + alo[0]) = S##a0; *(uint4*)(d_ + alo[1]) = S##a1; *(uint4*)(d_ + alo[2]) = S##a2; *(uint4*)(d_ + alo[3]) = S##a3; \
;     *(uint4*)(d_ + blo[0]) = S##b0; *(uint4*)(d_ + blo[1]) = S##b1; \
;     if (NBCH == 4) { *(uint4*)(d_ + blo[NBCH - 2]) = S##b2; *(uint4*)(d_ + blo[NBCH - 1]) = S##b3; } } while (0)
; template <int NJ, class RowA>
; DI void gemm_main(f32x16 (&acc)[2][NJ], const bf16_t* __restrict__ A, RowA rowA, size_t kstrideA, int m0, int Mmax,
;                   const bf16_t* __restrict__ Bt, size_t ldb, int n0, int nk, char* smem) {
;     ...
;   __syncthreads();
;   G_LOAD(x0, 0, 0);
;   G_LOAD(x1, 0, 1);
;   G_STORE(0, x0, 0);
;   __syncthreads();
; #pragma unroll 1
;   for (int kt = 0; kt < nk; kt += 2) {
;     G_LOAD(x0, 0, (kt + 2 < nk ? kt + 2 : nk - 1));
;     G_COMPUTE(0);
;     G_STORE(1, x1, 0);
;     __syncthreads();
;     G_LOAD(x1, 0, (kt + 3 < nk ? kt + 3 : nk - 1));
;     G_COMPUTE(1);
;     G_STORE(0, x0, 0);
;     __syncthreads();
;   }
.LBB0_12:
	s_cmp_lt_i32 s3, 12
	s_cbranch_scc0 .Lpeel_tail_12
	ds_read_b128 v[166:169], v0
	ds_read_b128 v[170:173], v139 offset:18432
	ds_read_b128 v[174:177], v139 offset:23040
	ds_read_b128 v[178:181], v0 offset:4608
	s_add_i32 s4, s3, 4
	s_min_u32 s4, s4, 15
	s_lshl_b32 s14, s4, 7
	v_lshl_add_u64 v[98:99], v[122:123], 0, s[14:15]
	v_lshl_add_u64 v[102:103], v[124:125], 0, s[14:15]
	v_lshl_add_u64 v[106:107], v[126:127], 0, s[14:15]
	v_lshl_add_u64 v[110:111], v[128:129], 0, s[14:15]
	v_lshl_add_u64 v[114:115], v[130:131], 0, s[14:15]
	v_lshl_add_u64 v[118:119], v[132:133], 0, s[14:15]
	s_add_i32 s3, s3, 2
	v_lshl_add_u64 v[158:159], v[134:135], 0, s[14:15]
	v_lshl_add_u64 v[160:161], v[136:137], 0, s[14:15]
	s_setprio 1
	ds_read_b128 v[182:185], v0 offset:32
	ds_read_b128 v[186:189], v139 offset:18464
	ds_read_b128 v[190:193], v139 offset:23072
	ds_read_b128 v[194:197], v0 offset:4640
	s_waitcnt lgkmcnt(4)
	v_mfma_f32_32x32x16_bf16 v[50:65], v[166:169], v[170:173], v[50:65]
	global_load_dwordx4 v[98:101], v[98:99], off
	v_mfma_f32_32x32x16_bf16 v[34:49], v[166:169], v[174:177], v[34:49]
	global_load_dwordx4 v[102:105], v[102:103], off
	v_mfma_f32_32x32x16_bf16 v[18:33], v[178:181], v[170:173], v[18:33]
	global_load_dwordx4 v[106:109], v[106:107], off
	v_mfma_f32_32x32x16_bf16 v[2:17], v[178:181], v[174:177], v[2:17]
	global_load_dwordx4 v[110:113], v[110:111], off
	ds_read_b128 v[166:169], v0 offset:64
	ds_read_b128 v[170:173], v139 offset:18496
	ds_read_b128 v[174:177], v139 offset:23104
	ds_read_b128 v[178:181], v0 offset:4672
	s_waitcnt lgkmcnt(4)
	v_mfma_f32_32x32x16_bf16 v[50:65], v[182:185], v[186:189], v[50:65]
	global_load_dwordx4 v[114:117], v[114:115], off
	s_waitcnt vmcnt(5)
	ds_write_b128 v138, v[78:81] offset:36864
	v_mfma_f32_32x32x16_bf16 v[34:49], v[182:185], v[190:193], v[34:49]
	global_load_dwordx4 v[118:121], v[118:119], off
	ds_write_b128 v140, v[86:89] offset:36864
	v_mfma_f32_32x32x16_bf16 v[18:33], v[194:197], v[186:189], v[18:33]
	global_load_dwordx4 v[146:149], v[160:161], off
	ds_write_b128 v142, v[90:93] offset:36864
	v_mfma_f32_32x32x16_bf16 v[2:17], v[194:197], v[190:193], v[2:17]
	global_load_dwordx4 v[150:153], v[158:159], off
	ds_write_b128 v144, v[94:97] offset:36864
	ds_read_b128 v[182:185], v0 offset:96
	ds_read_b128 v[186:189], v139 offset:18528
	ds_read_b128 v[190:193], v139 offset:23136
	ds_read_b128 v[194:197], v0 offset:4704
	s_waitcnt lgkmcnt(8)
	v_mfma_f32_32x32x16_bf16 v[50:65], v[166:169], v[170:173], v[50:65]
	ds_write_b128 v138, v[74:77] offset:55296
	v_mfma_f32_32x32x16_bf16 v[34:49], v[166:169], v[174:177], v[34:49]
	ds_write_b128 v140, v[82:85] offset:55296
	v_mfma_f32_32x32x16_bf16 v[18:33], v[178:181], v[170:173], v[18:33]
	ds_write_b128 v142, v[66:69] offset:55296
	v_mfma_f32_32x32x16_bf16 v[2:17], v[178:181], v[174:177], v[2:17]
	ds_write_b128 v144, v[70:73] offset:55296
	s_waitcnt lgkmcnt(4)
	v_mfma_f32_32x32x16_bf16 v[50:65], v[182:185], v[186:189], v[50:65]
	s_min_u32 s4, s3, 12
	s_lshl_b32 s14, s4, 7
	v_mfma_f32_32x32x16_bf16 v[34:49], v[182:185], v[190:193], v[34:49]
	v_lshl_add_u64 v[66:67], v[122:123], 0, s[14:15]
	v_lshl_add_u64 v[68:69], v[124:125], 0, s[14:15]
	v_mfma_f32_32x32x16_bf16 v[18:33], v[194:197], v[186:189], v[18:33]
	v_lshl_add_u64 v[70:71], v[126:127], 0, s[14:15]
	v_lshl_add_u64 v[72:73], v[128:129], 0, s[14:15]
	v_mfma_f32_32x32x16_bf16 v[2:17], v[194:197], v[190:193], v[2:17]
	v_lshl_add_u64 v[74:75], v[130:131], 0, s[14:15]
	v_lshl_add_u64 v[82:83], v[132:133], 0, s[14:15]
	s_setprio 0
	s_waitcnt lgkmcnt(0)
	s_barrier
	ds_read_b128 v[166:169], v0 offset:36864
	ds_read_b128 v[170:173], v139 offset:55296
	ds_read_b128 v[174:177], v139 offset:59904
	ds_read_b128 v[178:181], v0 offset:41472
	v_lshl_add_u64 v[154:155], v[134:135], 0, s[14:15]
	v_lshl_add_u64 v[156:157], v[136:137], 0, s[14:15]
	s_setprio 1
	ds_read_b128 v[182:185], v0 offset:36896
	ds_read_b128 v[186:189], v139 offset:55328
	ds_read_b128 v[190:193], v139 offset:59936
	ds_read_b128 v[194:197], v0 offset:41504
	s_waitcnt lgkmcnt(4)
	v_mfma_f32_32x32x16_bf16 v[50:65], v[166:169], v[170:173], v[50:65]
	global_load_dwordx4 v[78:81], v[66:67], off offset:384
	v_mfma_f32_32x32x16_bf16 v[34:49], v[166:169], v[174:177], v[34:49]
	global_load_dwordx4 v[86:89], v[68:69], off offset:384
	v_mfma_f32_32x32x16_bf16 v[18:33], v[178:181], v[170:173], v[18:33]
	global_load_dwordx4 v[90:93], v[70:71], off offset:384
	v_mfma_f32_32x32x16_bf16 v[2:17], v[178:181], v[174:177], v[2:17]
	global_load_dwordx4 v[94:97], v[72:73], off offset:384
	ds_read_b128 v[166:169], v0 offset:36928
	ds_read_b128 v[170:173], v139 offset:55360
	ds_read_b128 v[174:177], v139 offset:59968
	ds_read_b128 v[178:181], v0 offset:41536
	s_waitcnt lgkmcnt(4)
	v_mfma_f32_32x32x16_bf16 v[50:65], v[182:185], v[186:189], v[50:65]
	global_load_dwordx4 v[74:77], v[74:75], off offset:384
	s_waitcnt vmcnt(5)
	ds_write_b128 v138, v[98:101]
	v_mfma_f32_32x32x16_bf16 v[34:49], v[182:185], v[190:193], v[34:49]
	global_load_dwordx4 v[82:85], v[82:83], off offset:384
	ds_write_b128 v140, v[102:105]
	v_mfma_f32_32x32x16_bf16 v[18:33], v[194:197], v[186:189], v[18:33]
	global_load_dwordx4 v[66:69], v[154:155], off offset:384
	ds_write_b128 v142, v[106:109]
	v_mfma_f32_32x32x16_bf16 v[2:17], v[194:197], v[190:193], v[2:17]
	global_load_dwordx4 v[70:73], v[156:157], off offset:384
	ds_write_b128 v144, v[110:113]
	ds_read_b128 v[182:185], v0 offset:36960
	ds_read_b128 v[186:189], v139 offset:55392
	ds_read_b128 v[190:193], v139 offset:60000
	ds_read_b128 v[194:197], v0 offset:41568
	s_waitcnt lgkmcnt(8)
	v_mfma_f32_32x32x16_bf16 v[50:65], v[166:169], v[170:173], v[50:65]
	ds_write_b128 v138, v[114:117] offset:18432
	v_mfma_f32_32x32x16_bf16 v[34:49], v[166:169], v[174:177], v[34:49]
	ds_write_b128 v140, v[118:121] offset:18432
	v_mfma_f32_32x32x16_bf16 v[18:33], v[178:181], v[170:173], v[18:33]
	ds_write_b128 v142, v[150:153] offset:18432
	v_mfma_f32_32x32x16_bf16 v[2:17], v[178:181], v[174:177], v[2:17]
	ds_write_b128 v144, v[146:149] offset:18432
	s_waitcnt lgkmcnt(4)
	v_mfma_f32_32x32x16_bf16 v[50:65], v[182:185], v[186:189], v[50:65]
	s_cmp_lt_u32 s3, 14
	v_mfma_f32_32x32x16_bf16 v[34:49], v[182:185], v[190:193], v[34:49]
	v_mfma_f32_32x32x16_bf16 v[18:33], v[194:197], v[186:189], v[18:33]
	v_mfma_f32_32x32x16_bf16 v[2:17], v[194:197], v[190:193], v[2:17]
	s_setprio 0
	s_waitcnt lgkmcnt(0)
	s_barrier
	s_branch .LBB0_12
; #define G_STORE(ST, S, unused) do { char* d_ = smem + (ST) * STAGE; \
;     *(uint4*)(d_ + alo[0]) = S##a0; *(uint4*)(d_ + alo[1]) = S##a1; *(uint4*)(d_ + alo[2]) = S##a2; *(uint4*)(d_ + alo[3]) = S##a3; \
;     *(uint4*)(d_ + blo[0]) = S##b0; *(uint4*)(d_ + blo[1]) = S##b1; \
;     if (NBCH == 4) { *(uint4*)(d_ + blo[NBCH - 2]) = S##b2; *(uint4*)(d_ + blo[NBCH - 1]) = S##b3; } } while (0)
; template <int NJ, class RowA>
; DI void gemm_main(f32x16 (&acc)[2][NJ], const bf16_t* __restrict__ A, RowA rowA, size_t kstrideA, int m0, int Mmax,
;                   const bf16_t* __restrict__ Bt, size_t ldb, int n0, int nk, char* smem) {
;     ...
;   __syncthreads();
;   G_LOAD(x0, 0, 0);
;   G_LOAD(x1, 0, 1);
;   G_STORE(0, x0, 0);
;   __syncthreads();
; #pragma unroll 1
;   for (int kt = 0; kt < nk; kt += 2) {
;     G_LOAD(x0, 0, (kt + 2 < nk ? kt + 2 : nk - 1));
;     G_COMPUTE(0);
;     G_STORE(1, x1, 0);
;     __syncthreads();
;     G_LOAD(x1, 0, (kt + 3 < nk ? kt + 3 : nk - 1));
;     G_COMPUTE(1);
;     G_STORE(0, x0, 0);
;     __syncthreads();
;   }
.Lpeel_tail_12:
	ds_read_b128 v[166:169], v0
	ds_read_b128 v[170:173], v139 offset:18432
	ds_read_b128 v[174:177], v139 offset:23040
	ds_read_b128 v[178:181], v0 offset:4608
	s_add_i32 s4, s3, 4
	s_min_u32 s4, s4, 15
	s_lshl_b32 s14, s4, 7
	v_lshl_add_u64 v[98:99], v[122:123], 0, s[14:15]
	v_lshl_add_u64 v[102:103], v[124:125], 0, s[14:15]
	v_lshl_add_u64 v[106:107], v[126:127], 0, s[14:15]
	v_lshl_add_u64 v[110:111], v[128:129], 0, s[14:15]
	v_lshl_add_u64 v[114:115], v[130:131], 0, s[14:15]
	v_lshl_add_u64 v[118:119], v[132:133], 0, s[14:15]
	s_add_i32 s3, s3, 2
	v_lshl_add_u64 v[158:159], v[134:135], 0, s[14:15]
	v_lshl_add_u64 v[160:161], v[136:137], 0, s[14:15]
	s_setprio 1
	ds_read_b128 v[182:185], v0 offset:32
	ds_read_b128 v[186:189], v139 offset:18464
	ds_read_b128 v[190:193], v139 offset:23072
	ds_read_b128 v[194:197], v0 offset:4640
	s_waitcnt lgkmcnt(4)
	v_mfma_f32_32x32x16_bf16 v[50:65], v[166:169], v[170:173], v[50:65]
	v_mfma_f32_32x32x16_bf16 v[34:49], v[166:169], v[174:177], v[34:49]
	v_mfma_f32_32x32x16_bf16 v[18:33], v[178:181], v[170:173], v[18:33]
	v_mfma_f32_32x32x16_bf16 v[2:17], v[178:181], v[174:177], v[2:17]
	ds_read_b128 v[166:169], v0 offset:64
	ds_read_b128 v[170:173], v139 offset:18496
	ds_read_b128 v[174:177], v139 offset:23104
	ds_read_b128 v[178:181], v0 offset:4672
	s_waitcnt lgkmcnt(4)
	v_mfma_f32_32x32x16_bf16 v[50:65], v[182:185], v[186:189], v[50:65]
	v_mfma_f32_32x32x16_bf16 v[34:49], v[182:185], v[190:193], v[34:49]
	v_mfma_f32_32x32x16_bf16 v[18:33], v[194:197], v[186:189], v[18:33]
	v_mfma_f32_32x32x16_bf16 v[2:17], v[194:197], v[190:193], v[2:17]
	ds_read_b128 v[182:185], v0 offset:96
	ds_read_b128 v[186:189], v139 offset:18528
	ds_read_b128 v[190:193], v139 offset:23136
	ds_read_b128 v[194:197], v0 offset:4704
	s_waitcnt lgkmcnt(4)
	v_mfma_f32_32x32x16_bf16 v[50:65], v[166:169], v[170:173], v[50:65]
	s_waitcnt vmcnt(0)
	ds_write_b128 v138, v[78:81] offset:36864
	v_mfma_f32_32x32x16_bf16 v[34:49], v[166:169], v[174:177], v[34:49]
	ds_write_b128 v140, v[86:89] offset:36864
	v_mfma_f32_32x32x16_bf16 v[18:33], v[178:181], v[170:173], v[18:33]
	ds_write_b128 v142, v[90:93] offset:36864
	v_mfma_f32_32x32x16_bf16 v[2:17], v[178:181], v[174:177], v[2:17]
	ds_write_b128 v144, v[94:97] offset:36864
	s_waitcnt lgkmcnt(4)
	v_mfma_f32_32x32x16_bf16 v[50:65], v[182:185], v[186:189], v[50:65]
	ds_write_b128 v138, v[74:77] offset:55296
	v_mfma_f32_32x32x16_bf16 v[34:49], v[182:185], v[190:193], v[34:49]
	ds_write_b128 v140, v[82:85] offset:55296
	v_mfma_f32_32x32x16_bf16 v[18:33], v[194:197], v[186:189], v[18:33]
	ds_write_b128 v142, v[66:69] offset:55296
	v_mfma_f32_32x32x16_bf16 v[2:17], v[194:197], v[190:193], v[2:17]
	ds_write_b128 v144, v[70:73] offset:55296
	s_setprio 0
	s_min_u32 s4, s3, 12
	s_lshl_b32 s14, s4, 7
	v_lshl_add_u64 v[66:67], v[122:123], 0, s[14:15]
	v_lshl_add_u64 v[68:69], v[124:125], 0, s[14:15]
	v_lshl_add_u64 v[70:71], v[126:127], 0, s[14:15]
	v_lshl_add_u64 v[72:73], v[128:129], 0, s[14:15]
	v_lshl_add_u64 v[74:75], v[130:131], 0, s[14:15]
	v_lshl_add_u64 v[82:83], v[132:133], 0, s[14:15]
	s_waitcnt lgkmcnt(0)
	s_barrier
	ds_read_b128 v[166:169], v0 offset:36864
	ds_read_b128 v[170:173], v139 offset:55296
	ds_read_b128 v[174:177], v139 offset:59904
	ds_read_b128 v[178:181], v0 offset:41472
	v_lshl_add_u64 v[154:155], v[134:135], 0, s[14:15]
	v_lshl_add_u64 v[156:157], v[136:137], 0, s[14:15]
	s_setprio 1
	ds_read_b128 v[182:185], v0 offset:36896
	ds_read_b128 v[186:189], v139 offset:55328
	ds_read_b128 v[190:193], v139 offset:59936
	ds_read_b128 v[194:197], v0 offset:41504
	s_waitcnt lgkmcnt(4)
	v_mfma_f32_32x32x16_bf16 v[50:65], v[166:169], v[170:173], v[50:65]
	s_cmp_lt_u32 s3, 14
	v_mfma_f32_32x32x16_bf16 v[34:49], v[166:169], v[174:177], v[34:49]
	v_mfma_f32_32x32x16_bf16 v[18:33], v[178:181], v[170:173], v[18:33]
	v_mfma_f32_32x32x16_bf16 v[2:17], v[178:181], v[174:177], v[2:17]
	ds_read_b128 v[166:169], v0 offset:36928
	ds_read_b128 v[170:173], v139 offset:55360
	ds_read_b128 v[174:177], v139 offset:59968
	ds_read_b128 v[178:181], v0 offset:41536
	s_waitcnt lgkmcnt(4)
	v_mfma_f32_32x32x16_bf16 v[50:65], v[182:185], v[186:189], v[50:65]
	v_mfma_f32_32x32x16_bf16 v[34:49], v[182:185], v[190:193], v[34:49]
	v_mfma_f32_32x32x16_bf16 v[18:33], v[194:197], v[186:189], v[18:33]
	v_mfma_f32_32x32x16_bf16 v[2:17], v[194:197], v[190:193], v[2:17]
	ds_read_b128 v[182:185], v0 offset:36960
	ds_read_b128 v[186:189], v139 offset:55392
	ds_read_b128 v[190:193], v139 offset:60000
	ds_read_b128 v[194:197], v0 offset:41568
	s_waitcnt lgkmcnt(4)
	v_mfma_f32_32x32x16_bf16 v[50:65], v[166:169], v[170:173], v[50:65]
	v_mfma_f32_32x32x16_bf16 v[34:49], v[166:169], v[174:177], v[34:49]
	v_mfma_f32_32x32x16_bf16 v[18:33], v[178:181], v[170:173], v[18:33]
	v_mfma_f32_32x32x16_bf16 v[2:17], v[178:181], v[174:177], v[2:17]
	s_waitcnt lgkmcnt(0)
	v_mfma_f32_32x32x16_bf16 v[50:65], v[182:185], v[186:189], v[50:65]
	v_mfma_f32_32x32x16_bf16 v[34:49], v[182:185], v[190:193], v[34:49]
	v_mfma_f32_32x32x16_bf16 v[18:33], v[194:197], v[186:189], v[18:33]
	v_mfma_f32_32x32x16_bf16 v[2:17], v[194:197], v[190:193], v[2:17]
	s_setprio 0
	s_waitcnt lgkmcnt(0)
	s_barrier
; #define TIDX (tid_launder())
; DI int crow(int reg, int hh) { return (reg & 3) + 8 * (reg >> 2) + 4 * hh; }
; template <int NJ>
; DI void acc_to_ct(const f32x16 (&acc)[2][NJ], float* Ct) {
;   const int lane = TIDX & 63, wid = TIDX >> 6, wm = wid >> 1, wn = wid & 1;
;   const int r = lane & 31, hh = lane >> 5;
; #pragma unroll
;   for (int i = 0; i < 2; ++i)
; #pragma unroll
;     for (int j = 0; j < NJ; ++j)
; #pragma unroll
;       for (int e = 0; e < 16; ++e) Ct[(wm * 64 + i * 32 + crow(e, hh)) * 132 + wn * 32 * NJ + j * 32 + r] = acc[i][j][e];
;   __syncthreads();
; DI void outproj_tile(const Params& p, int l, int mt, int tn, char* smem) {
;     ...
;     const int tid = TIDX, c = (tid & 31) * 4, row0 = tid >> 5;
;     float4 xa[16];
; #pragma unroll
;     for (int q = 0; q < 16; ++q) xa[q] = *(const float4*)(xo + (size_t)(m0 + row0 + 8 * q) * 1024 + tn * 128 + c);
	v_mov_b32_e32 v0, v230
	s_waitcnt vmcnt(1)
	v_mov_b32_e32 v66, v230
	v_and_b32_e32 v67, 31, v0
	v_lshrrev_b32_e32 v0, 3, v0
	v_and_b32_e32 v0, 4, v0
	v_lshrrev_b32_e32 v68, 1, v66
	v_and_or_b32 v0, v68, s47, v0
	v_and_or_b32 v66, v66, 64, v67
	v_mul_lo_u32 v0, v0, s79
	v_lshl_add_u32 v0, v66, 2, v0
	ds_write2_b32 v0, v50, v34 offset1:32
	ds_write2_b32 v0, v51, v35 offset0:132 offset1:164
	v_add_u32_e32 v34, 0x400, v0
	ds_write2_b32 v34, v52, v36 offset0:8 offset1:40
	ds_write2_b32 v34, v53, v37 offset0:140 offset1:172
	v_add_u32_e32 v34, 0x1000, v0
	ds_write2_b32 v34, v54, v38 offset0:32 offset1:64
	ds_write2_b32 v34, v55, v39 offset0:164 offset1:196
	v_add_u32_e32 v34, 0x1400, v0
	ds_write2_b32 v34, v56, v40 offset0:40 offset1:72
	ds_write2_b32 v34, v57, v41 offset0:172 offset1:204
	v_add_u32_e32 v34, 0x2000, v0
	ds_write2_b32 v34, v58, v42 offset0:64 offset1:96
	ds_write2_b32 v34, v59, v43 offset0:196 offset1:228
	v_add_u32_e32 v34, 0x2400, v0
	ds_write2_b32 v34, v60, v44 offset0:72 offset1:104
	ds_write2_b32 v34, v61, v45 offset0:204 offset1:236
	v_add_u32_e32 v34, 0x3000, v0
	ds_write2_b32 v34, v62, v46 offset0:96 offset1:128
	v_add_u32_e32 v34, 0x3200, v0
	ds_write2_b32 v34, v63, v47 offset0:100 offset1:132
	v_add_u32_e32 v34, 0x3400, v0
	ds_write2_b32 v34, v64, v48 offset0:104 offset1:136
	v_add_u32_e32 v34, 0x3600, v0
	ds_write2_b32 v34, v65, v49 offset0:108 offset1:140
	v_add_u32_e32 v34, 0x4000, v0
	ds_write2_b32 v34, v18, v2 offset0:128 offset1:160
	v_add_u32_e32 v2, 0x4400, v0
	ds_write2_b32 v2, v19, v3 offset0:4 offset1:36
	ds_write2_b32 v2, v20, v4 offset0:136 offset1:168
	v_add_u32_e32 v2, 0x4800, v0
	ds_write2_b32 v2, v21, v5 offset0:12 offset1:44
	v_add_u32_e32 v2, 0x5000, v0
	ds_write2_b32 v2, v22, v6 offset0:160 offset1:192
	v_add_u32_e32 v2, 0x5400, v0
	ds_write2_b32 v2, v23, v7 offset0:36 offset1:68
	ds_write2_b32 v2, v24, v8 offset0:168 offset1:200
	v_add_u32_e32 v2, 0x5800, v0
	ds_write2_b32 v2, v25, v9 offset0:44 offset1:76
	v_add_u32_e32 v2, 0x6000, v0
	ds_write2_b32 v2, v26, v10 offset0:192 offset1:224
	v_add_u32_e32 v2, 0x6400, v0
	ds_write2_b32 v2, v27, v11 offset0:68 offset1:100
	ds_write2_b32 v2, v28, v12 offset0:200 offset1:232
	v_add_u32_e32 v2, 0x6800, v0
	ds_write2_b32 v2, v29, v13 offset0:76 offset1:108
	v_add_u32_e32 v2, 0x7200, v0
	ds_write2_b32 v2, v30, v14 offset0:96 offset1:128
	v_add_u32_e32 v2, 0x7400, v0
	ds_write2_b32 v2, v31, v15 offset0:100 offset1:132
	v_add_u32_e32 v2, 0x7600, v0
	v_add_u32_e32 v0, 0x7800, v0
	ds_write2_b32 v0, v33, v17 offset0:108 offset1:140
	v_mov_b32_e32 v0, v230
	ds_write2_b32 v2, v32, v16 offset0:104 offset1:136
	s_waitcnt lgkmcnt(0)
	s_barrier
	s_lshl_b32 s14, s2, 2
	v_ashrrev_i32_e32 v68, 5, v0
	v_readlane_b32 s2, v254, 3
	v_add_u32_e32 v2, s1, v68
	v_readlane_b32 s3, v254, 4
	s_add_u32 s2, s2, s14
	v_lshlrev_b32_e32 v0, 4, v0
	s_addc_u32 s3, s3, 0
	v_and_b32_e32 v0, 0x1f0, v0
	v_ashrrev_i32_e32 v3, 31, v2
	v_lshl_add_u64 v[4:5], s[2:3], 0, v[0:1]
	v_lshlrev_b64 v[8:9], 12, v[2:3]
	s_mov_b64 s[2:3], 0x18000
	v_lshl_add_u64 v[20:21], v[8:9], 0, s[2:3]
	s_mov_b64 s[2:3], 0x20000
	v_lshl_add_u64 v[24:25], v[8:9], 0, s[2:3]
	s_mov_b64 s[2:3], 0x28000
	v_lshl_add_u64 v[28:29], v[8:9], 0, s[2:3]
	s_mov_b64 s[2:3], 0x30000
	v_lshl_add_u64 v[32:33], v[8:9], 0, s[2:3]
	s_mov_b64 s[2:3], 0x38000
	v_lshl_add_u64 v[36:37], v[8:9], 0, s[2:3]
	s_mov_b64 s[2:3], 0x40000
	v_lshl_add_u64 v[40:41], v[8:9], 0, s[2:3]
	s_mov_b64 s[2:3], 0x48000
	v_lshl_add_u64 v[44:45], v[8:9], 0, s[2:3]
	s_mov_b64 s[2:3], 0x50000
	v_lshl_add_u64 v[48:49], v[8:9], 0, s[2:3]
	s_mov_b64 s[2:3], 0x58000
	v_lshl_add_u64 v[52:53], v[8:9], 0, s[2:3]
	s_mov_b64 s[2:3], 0x60000
	v_lshl_add_u64 v[56:57], v[8:9], 0, s[2:3]
	s_mov_b64 s[2:3], 0x68000
	v_lshl_add_u64 v[60:61], v[8:9], 0, s[2:3]
	s_mov_b64 s[2:3], 0x70000
	v_lshl_add_u64 v[64:65], v[8:9], 0, s[2:3]
	s_mov_b64 s[2:3], 0x78000
	v_readlane_b32 s16, v252, 9
	v_lshl_add_u64 v[12:13], v[8:9], 0, s[48:49]
	v_lshl_add_u64 v[16:17], v[8:9], 0, s[40:41]
	v_lshl_add_u64 v[66:67], v[8:9], 0, s[2:3]
	v_readlane_b32 s22, v252, 15
	v_readlane_b32 s23, v252, 16
	v_lshl_add_u64 v[62:63], v[4:5], 0, v[8:9]
	v_lshl_add_u64 v[58:59], v[4:5], 0, v[12:13]
	v_lshl_add_u64 v[54:55], v[4:5], 0, v[16:17]
	v_lshl_add_u64 v[50:51], v[4:5], 0, v[20:21]
	v_lshl_add_u64 v[46:47], v[4:5], 0, v[24:25]
	v_lshl_add_u64 v[42:43], v[4:5], 0, v[28:29]
	v_lshl_add_u64 v[38:39], v[4:5], 0, v[32:33]
	v_lshl_add_u64 v[34:35], v[4:5], 0, v[36:37]
	v_lshl_add_u64 v[30:31], v[4:5], 0, v[40:41]
	v_lshl_add_u64 v[26:27], v[4:5], 0, v[44:45]
	v_lshl_add_u64 v[22:23], v[4:5], 0, v[48:49]
	v_lshl_add_u64 v[18:19], v[4:5], 0, v[52:53]
	v_lshl_add_u64 v[14:15], v[4:5], 0, v[56:57]
	v_lshl_add_u64 v[10:11], v[4:5], 0, v[60:61]
	v_lshl_add_u64 v[6:7], v[4:5], 0, v[64:65]
	v_lshl_add_u64 v[2:3], v[4:5], 0, v[66:67]
	v_lshl_add_u64 v[4:5], s[22:23], 0, v[8:9]
	v_lshl_add_u64 v[4:5], v[4:5], 0, s[14:15]
	v_lshl_add_u64 v[96:97], v[4:5], 0, v[0:1]
	v_lshl_add_u64 v[4:5], s[22:23], 0, v[12:13]
	v_lshl_add_u64 v[4:5], v[4:5], 0, s[14:15]
	v_lshl_add_u64 v[94:95], v[4:5], 0, v[0:1]
	v_lshl_add_u64 v[4:5], s[22:23], 0, v[16:17]
	v_lshl_add_u64 v[4:5], v[4:5], 0, s[14:15]
	v_lshl_add_u64 v[92:93], v[4:5], 0, v[0:1]
	v_lshl_add_u64 v[4:5], s[22:23], 0, v[20:21]
	v_lshl_add_u64 v[4:5], v[4:5], 0, s[14:15]
	v_lshl_add_u64 v[90:91], v[4:5], 0, v[0:1]
	v_lshl_add_u64 v[4:5], s[22:23], 0, v[24:25]
	v_lshl_add_u64 v[4:5], v[4:5], 0, s[14:15]
	v_lshl_add_u64 v[88:89], v[4:5], 0, v[0:1]
	v_lshl_add_u64 v[4:5], s[22:23], 0, v[28:29]
	v_lshl_add_u64 v[4:5], v[4:5], 0, s[14:15]
	v_lshl_add_u64 v[86:87], v[4:5], 0, v[0:1]
	v_lshl_add_u64 v[4:5], s[22:23], 0, v[32:33]
	v_lshl_add_u64 v[4:5], v[4:5], 0, s[14:15]
	v_lshl_add_u64 v[84:85], v[4:5], 0, v[0:1]
	v_lshl_add_u64 v[4:5], s[22:23], 0, v[36:37]
	v_lshl_add_u64 v[4:5], v[4:5], 0, s[14:15]
	v_lshl_add_u64 v[82:83], v[4:5], 0, v[0:1]
	v_lshl_add_u64 v[4:5], s[22:23], 0, v[40:41]
	v_lshl_add_u64 v[4:5], v[4:5], 0, s[14:15]
	v_lshl_add_u64 v[80:81], v[4:5], 0, v[0:1]
	v_lshl_add_u64 v[4:5], s[22:23], 0, v[44:45]
	v_lshl_add_u64 v[4:5], v[4:5], 0, s[14:15]
	v_lshl_add_u64 v[78:79], v[4:5], 0, v[0:1]
	v_lshl_add_u64 v[4:5], s[22:23], 0, v[48:49]
	v_lshl_add_u64 v[4:5], v[4:5], 0, s[14:15]
	v_lshl_add_u64 v[76:77], v[4:5], 0, v[0:1]
	v_lshl_add_u64 v[4:5], s[22:23], 0, v[52:53]
	v_lshl_add_u64 v[4:5], v[4:5], 0, s[14:15]
	v_lshl_add_u64 v[74:75], v[4:5], 0, v[0:1]
	v_lshl_add_u64 v[4:5], s[22:23], 0, v[56:57]
	v_lshl_add_u64 v[4:5], v[4:5], 0, s[14:15]
	s_waitcnt vmcnt(0)
; #define TIDX (tid_launder())
; DI void outproj_tile(const Params& p, int l, int mt, int tn, char* smem) {
;     ...
;     const int tid = TIDX, c = (tid & 31) * 4, row0 = tid >> 5;
;     float4 xa[16];
; #pragma unroll
;     for (int q = 0; q < 16; ++q) xa[q] = *(const float4*)(xo + (size_t)(m0 + row0 + 8 * q) * 1024 + tn * 128 + c);
; #pragma unroll
;     for (int q = 0; q < 16; ++q) {
;       const float4 cc = *(const float4*)(Ct + (row0 + 8 * q) * 132 + c);
;       *(float4*)(p.out + (size_t)(m0 + row0 + 8 * q) * 1024 + tn * 128 + c) = make_float4(xa[q].x + cc.x, xa[q].y + cc.y, xa[q].z + cc.z, xa[q].w + cc.w);
;     }
;   }
;   __syncthreads();
	v_lshl_add_u64 v[72:73], v[4:5], 0, v[0:1]
	v_lshl_add_u64 v[4:5], s[22:23], 0, v[60:61]
	v_lshl_add_u64 v[4:5], v[4:5], 0, s[14:15]
	v_lshl_add_u64 v[70:71], v[4:5], 0, v[0:1]
	v_lshl_add_u64 v[4:5], s[22:23], 0, v[64:65]
	v_lshl_add_u64 v[4:5], v[4:5], 0, s[14:15]
	v_mad_u64_u32 v[98:99], s[2:3], v68, s79, v[0:1]
	v_lshl_add_u64 v[68:69], v[4:5], 0, v[0:1]
	v_lshl_add_u64 v[4:5], s[22:23], 0, v[66:67]
	v_lshl_add_u64 v[4:5], v[4:5], 0, s[14:15]
	v_lshl_add_u64 v[66:67], v[4:5], 0, v[0:1]
	global_load_dwordx4 v[2:5], v[2:3], off
	ds_read_b128 v[100:103], v98 offset:63360
	global_load_dwordx4 v[6:9], v[6:7], off
	v_readlane_b32 s1, v250, 60
	global_load_dwordx4 v[10:13], v[10:11], off
	s_add_i32 s0, s0, s1
	global_load_dwordx4 v[14:17], v[14:15], off
	s_cmpk_gt_u32 s0, 0xff
	global_load_dwordx4 v[18:21], v[18:19], off
	v_readlane_b32 s17, v252, 10
	global_load_dwordx4 v[22:25], v[22:23], off
	v_readlane_b32 s18, v252, 11
	global_load_dwordx4 v[26:29], v[26:27], off
	v_readlane_b32 s19, v252, 12
	global_load_dwordx4 v[30:33], v[30:31], off
	v_readlane_b32 s20, v252, 13
	global_load_dwordx4 v[34:37], v[34:35], off
	v_readlane_b32 s21, v252, 14
	global_load_dwordx4 v[38:41], v[38:39], off
	v_readlane_b32 s24, v252, 17
	global_load_dwordx4 v[42:45], v[42:43], off
	v_readlane_b32 s25, v252, 18
	global_load_dwordx4 v[46:49], v[46:47], off
	v_readlane_b32 s26, v252, 19
	global_load_dwordx4 v[50:53], v[50:51], off
	v_readlane_b32 s27, v252, 20
	global_load_dwordx4 v[54:57], v[54:55], off
	v_readlane_b32 s28, v252, 21
	global_load_dwordx4 v[58:61], v[58:59], off
	v_readlane_b32 s29, v252, 22
	global_load_dwordx4 v[62:65], v[62:63], off
	v_readlane_b32 s30, v252, 23
	v_readlane_b32 s31, v252, 24
	s_waitcnt vmcnt(15) lgkmcnt(0)
	v_pk_add_f32 v[2:3], v[2:3], v[100:101]
	v_pk_add_f32 v[4:5], v[4:5], v[102:103]
	ds_read_b128 v[100:103], v98 offset:59136
	s_waitcnt vmcnt(14) lgkmcnt(0)
	v_pk_add_f32 v[6:7], v[6:7], v[100:101]
	v_pk_add_f32 v[8:9], v[8:9], v[102:103]
	ds_read_b128 v[100:103], v98 offset:54912
	s_waitcnt vmcnt(13) lgkmcnt(0)
	v_pk_add_f32 v[10:11], v[10:11], v[100:101]
	v_pk_add_f32 v[12:13], v[12:13], v[102:103]
	ds_read_b128 v[100:103], v98 offset:50688
	s_waitcnt vmcnt(12) lgkmcnt(0)
	v_pk_add_f32 v[14:15], v[14:15], v[100:101]
	v_pk_add_f32 v[16:17], v[16:17], v[102:103]
	ds_read_b128 v[100:103], v98 offset:46464
	s_waitcnt vmcnt(11) lgkmcnt(0)
	v_pk_add_f32 v[18:19], v[18:19], v[100:101]
	v_pk_add_f32 v[20:21], v[20:21], v[102:103]
	ds_read_b128 v[100:103], v98 offset:42240
	s_waitcnt vmcnt(10) lgkmcnt(0)
	v_pk_add_f32 v[22:23], v[22:23], v[100:101]
	v_pk_add_f32 v[24:25], v[24:25], v[102:103]
	ds_read_b128 v[100:103], v98 offset:38016
	s_waitcnt vmcnt(9) lgkmcnt(0)
	v_pk_add_f32 v[26:27], v[26:27], v[100:101]
	v_pk_add_f32 v[28:29], v[28:29], v[102:103]
	ds_read_b128 v[100:103], v98 offset:33792
	s_waitcnt vmcnt(8) lgkmcnt(0)
	v_pk_add_f32 v[30:31], v[30:31], v[100:101]
	v_pk_add_f32 v[32:33], v[32:33], v[102:103]
	ds_read_b128 v[100:103], v98 offset:29568
	s_waitcnt vmcnt(7) lgkmcnt(0)
	v_pk_add_f32 v[34:35], v[34:35], v[100:101]
	v_pk_add_f32 v[36:37], v[36:37], v[102:103]
	ds_read_b128 v[100:103], v98 offset:25344
	s_waitcnt vmcnt(6) lgkmcnt(0)
	v_pk_add_f32 v[38:39], v[38:39], v[100:101]
	v_pk_add_f32 v[40:41], v[40:41], v[102:103]
	ds_read_b128 v[100:103], v98 offset:21120
	s_waitcnt vmcnt(5) lgkmcnt(0)
	v_pk_add_f32 v[42:43], v[42:43], v[100:101]
	v_pk_add_f32 v[44:45], v[44:45], v[102:103]
	ds_read_b128 v[100:103], v98 offset:16896
	s_waitcnt vmcnt(4) lgkmcnt(0)
	v_pk_add_f32 v[46:47], v[46:47], v[100:101]
	v_pk_add_f32 v[48:49], v[48:49], v[102:103]
	ds_read_b128 v[100:103], v98 offset:12672
	s_waitcnt vmcnt(3) lgkmcnt(0)
	v_pk_add_f32 v[50:51], v[50:51], v[100:101]
	v_pk_add_f32 v[52:53], v[52:53], v[102:103]
	ds_read_b128 v[100:103], v98 offset:8448
	s_waitcnt vmcnt(2) lgkmcnt(0)
	v_pk_add_f32 v[54:55], v[54:55], v[100:101]
	v_pk_add_f32 v[56:57], v[56:57], v[102:103]
	ds_read_b128 v[100:103], v98 offset:4224
	s_waitcnt vmcnt(1) lgkmcnt(0)
	v_pk_add_f32 v[58:59], v[58:59], v[100:101]
	ds_read_b128 v[98:101], v98
	v_pk_add_f32 v[60:61], v[60:61], v[102:103]
	s_waitcnt vmcnt(0) lgkmcnt(0)
	v_pk_add_f32 v[62:63], v[62:63], v[98:99]
	v_pk_add_f32 v[64:65], v[64:65], v[100:101]
	global_store_dwordx4 v[96:97], v[62:65], off
	global_store_dwordx4 v[94:95], v[58:61], off
	global_store_dwordx4 v[92:93], v[54:57], off
	global_store_dwordx4 v[90:91], v[50:53], off
	global_store_dwordx4 v[88:89], v[46:49], off
	global_store_dwordx4 v[86:87], v[42:45], off
	global_store_dwordx4 v[84:85], v[38:41], off
	global_store_dwordx4 v[82:83], v[34:37], off
	global_store_dwordx4 v[80:81], v[30:33], off
	global_store_dwordx4 v[78:79], v[26:29], off
	global_store_dwordx4 v[76:77], v[22:25], off
	global_store_dwordx4 v[74:75], v[18:21], off
	global_store_dwordx4 v[72:73], v[14:17], off
	global_store_dwordx4 v[70:71], v[10:13], off
	global_store_dwordx4 v[68:69], v[6:9], off
	global_store_dwordx4 v[66:67], v[2:5], off
	s_barrier
	s_cbranch_scc0 .LBB0_11

; #define G_STORE(ST, S, unused) do { char* d_ = smem + (ST) * STAGE; \
;     *(uint4*)(d_ + alo[0]) = S##a0; *(uint4*)(d_ + alo[1]) = S##a1; *(uint4*)(d_ + alo[2]) = S##a2; *(uint4*)(d_ + alo[3]) = S##a3; \
;     *(uint4*)(d_ + blo[0]) = S##b0; *(uint4*)(d_ + blo[1]) = S##b1; \
;     if (NBCH == 4) { *(uint4*)(d_ + blo[NBCH - 2]) = S##b2; *(uint4*)(d_ + blo[NBCH - 1]) = S##b3; } } while (0)
; template <int NJ, class RowA>
; DI void gemm_main(f32x16 (&acc)[2][NJ], const bf16_t* __restrict__ A, RowA rowA, size_t kstrideA, int m0, int Mmax,
;                   const bf16_t* __restrict__ Bt, size_t ldb, int n0, int nk, char* smem) {
;     ...
;   __syncthreads();
;   G_LOAD(x0, 0, 0);
;   G_LOAD(x1, 0, 1);
;   G_STORE(0, x0, 0);
;   __syncthreads();
; #pragma unroll 1
;   for (int kt = 0; kt < nk; kt += 2) {
;     G_LOAD(x0, 0, (kt + 2 < nk ? kt + 2 : nk - 1));
;     G_COMPUTE(0);
;     G_STORE(1, x1, 0);
;     __syncthreads();
;     G_LOAD(x1, 0, (kt + 3 < nk ? kt + 3 : nk - 1));
;     G_COMPUTE(1);
;     G_STORE(0, x0, 0);
;     __syncthreads();
;   }
.LBB0_19:
	s_cmp_lt_i32 s4, 12
	s_cbranch_scc0 .Lpeel_tail_19
	ds_read_b128 v[176:179], v0
	ds_read_b128 v[180:183], v71 offset:18432
	ds_read_b128 v[184:187], v0 offset:4608
	s_add_i32 s5, s4, 4
	s_min_u32 s5, s5, 15
	s_lshl_b32 s14, s5, 7
	v_lshl_add_u64 v[78:79], v[58:59], 0, s[14:15]
	v_lshl_add_u64 v[82:83], v[60:61], 0, s[14:15]
	v_lshl_add_u64 v[86:87], v[62:63], 0, s[14:15]
	v_lshl_add_u64 v[122:123], v[64:65], 0, s[14:15]
	v_lshl_add_u64 v[126:127], v[66:67], 0, s[14:15]
	v_lshl_add_u64 v[130:131], v[68:69], 0, s[14:15]
	s_add_i32 s4, s4, 2
	s_setprio 1
	ds_read_b128 v[188:191], v0 offset:32
	ds_read_b128 v[192:195], v71 offset:18464
	ds_read_b128 v[196:199], v0 offset:4640
	s_waitcnt lgkmcnt(3)
	v_mfma_f32_32x32x16_bf16 v[18:33], v[176:179], v[180:183], v[18:33]
	global_load_dwordx4 v[78:81], v[78:79], off
	s_nop 0
	global_load_dwordx4 v[82:85], v[82:83], off
	v_mfma_f32_32x32x16_bf16 v[2:17], v[184:187], v[180:183], v[2:17]
	global_load_dwordx4 v[86:89], v[86:87], off
	ds_read_b128 v[176:179], v0 offset:64
	ds_read_b128 v[180:183], v71 offset:18496
	ds_read_b128 v[184:187], v0 offset:4672
	s_waitcnt lgkmcnt(3)
	v_mfma_f32_32x32x16_bf16 v[18:33], v[188:191], v[192:195], v[18:33]
	global_load_dwordx4 v[122:125], v[122:123], off
	s_nop 0
	global_load_dwordx4 v[126:129], v[126:127], off
	s_waitcnt vmcnt(5)
	ds_write_b128 v70, v[34:37] offset:27648
	ds_write_b128 v72, v[38:41] offset:27648
	v_mfma_f32_32x32x16_bf16 v[2:17], v[196:199], v[192:195], v[2:17]
	global_load_dwordx4 v[130:133], v[130:131], off
	ds_write_b128 v74, v[42:45] offset:27648
	ds_read_b128 v[188:191], v0 offset:96
	ds_read_b128 v[192:195], v71 offset:18528
	ds_read_b128 v[196:199], v0 offset:4704
	s_waitcnt lgkmcnt(6)
	v_mfma_f32_32x32x16_bf16 v[18:33], v[176:179], v[180:183], v[18:33]
	ds_write_b128 v76, v[54:57] offset:27648
	ds_write_b128 v70, v[46:49] offset:46080
	v_mfma_f32_32x32x16_bf16 v[2:17], v[184:187], v[180:183], v[2:17]
	ds_write_b128 v72, v[50:53] offset:46080
	s_waitcnt lgkmcnt(3)
	v_mfma_f32_32x32x16_bf16 v[18:33], v[188:191], v[192:195], v[18:33]
	s_min_u32 s5, s4, 12
	s_lshl_b32 s14, s5, 7
	v_lshl_add_u64 v[34:35], v[58:59], 0, s[14:15]
	v_lshl_add_u64 v[38:39], v[60:61], 0, s[14:15]
	v_mfma_f32_32x32x16_bf16 v[2:17], v[196:199], v[192:195], v[2:17]
	v_lshl_add_u64 v[42:43], v[62:63], 0, s[14:15]
	v_lshl_add_u64 v[46:47], v[64:65], 0, s[14:15]
	v_lshl_add_u64 v[48:49], v[66:67], 0, s[14:15]
	v_lshl_add_u64 v[50:51], v[68:69], 0, s[14:15]
	s_setprio 0
	s_waitcnt lgkmcnt(0)
	s_barrier
	ds_read_b128 v[176:179], v0 offset:27648
	ds_read_b128 v[180:183], v71 offset:46080
	ds_read_b128 v[184:187], v0 offset:32256
	s_setprio 1
	ds_read_b128 v[188:191], v0 offset:27680
	ds_read_b128 v[192:195], v71 offset:46112
	ds_read_b128 v[196:199], v0 offset:32288
	s_waitcnt lgkmcnt(3)
	v_mfma_f32_32x32x16_bf16 v[18:33], v[176:179], v[180:183], v[18:33]
	global_load_dwordx4 v[34:37], v[34:35], off offset:384
	s_nop 0
	global_load_dwordx4 v[38:41], v[38:39], off offset:384
	v_mfma_f32_32x32x16_bf16 v[2:17], v[184:187], v[180:183], v[2:17]
	global_load_dwordx4 v[42:45], v[42:43], off offset:384
	ds_read_b128 v[176:179], v0 offset:27712
	ds_read_b128 v[180:183], v71 offset:46144
	ds_read_b128 v[184:187], v0 offset:32320
	s_waitcnt lgkmcnt(3)
	v_mfma_f32_32x32x16_bf16 v[18:33], v[188:191], v[192:195], v[18:33]
	global_load_dwordx4 v[54:57], v[46:47], off offset:384
	s_nop 0
	global_load_dwordx4 v[46:49], v[48:49], off offset:384
	s_waitcnt vmcnt(5)
	ds_write_b128 v70, v[78:81]
	ds_write_b128 v72, v[82:85]
	v_mfma_f32_32x32x16_bf16 v[2:17], v[196:199], v[192:195], v[2:17]
	global_load_dwordx4 v[50:53], v[50:51], off offset:384
	ds_write_b128 v74, v[86:89]
	ds_read_b128 v[188:191], v0 offset:27744
	ds_read_b128 v[192:195], v71 offset:46176
	ds_read_b128 v[196:199], v0 offset:32352
	s_waitcnt lgkmcnt(6)
	v_mfma_f32_32x32x16_bf16 v[18:33], v[176:179], v[180:183], v[18:33]
	ds_write_b128 v76, v[122:125]
	ds_write_b128 v70, v[126:129] offset:18432
	v_mfma_f32_32x32x16_bf16 v[2:17], v[184:187], v[180:183], v[2:17]
	ds_write_b128 v72, v[130:133] offset:18432
	s_waitcnt lgkmcnt(3)
	v_mfma_f32_32x32x16_bf16 v[18:33], v[188:191], v[192:195], v[18:33]
	s_cmp_lt_u32 s4, 14
	v_mfma_f32_32x32x16_bf16 v[2:17], v[196:199], v[192:195], v[2:17]
	s_setprio 0
	s_waitcnt lgkmcnt(0)
	s_barrier
	s_branch .LBB0_19
; #define TIDX (tid_launder())
; #define G_STORE(ST, S, unused) do { char* d_ = smem + (ST) * STAGE; \
;     *(uint4*)(d_ + alo[0]) = S##a0; *(uint4*)(d_ + alo[1]) = S##a1; *(uint4*)(d_ + alo[2]) = S##a2; *(uint4*)(d_ + alo[3]) = S##a3; \
;     *(uint4*)(d_ + blo[0]) = S##b0; *(uint4*)(d_ + blo[1]) = S##b1; \
;     if (NBCH == 4) { *(uint4*)(d_ + blo[NBCH - 2]) = S##b2; *(uint4*)(d_ + blo[NBCH - 1]) = S##b3; } } while (0)
; template <int NJ, class RowA>
; DI void gemm_main(f32x16 (&acc)[2][NJ], const bf16_t* __restrict__ A, RowA rowA, size_t kstrideA, int m0, int Mmax,
;                   const bf16_t* __restrict__ Bt, size_t ldb, int n0, int nk, char* smem) {
;     ...
;   const int tid = TIDX, lane = tid & 63, wid = tid >> 6, wm = wid >> 1, wn = wid & 1;
;   const int r = lane & 31, hh = lane >> 5;
;   const bf16_t* ap[4]; const bf16_t* bp[NBCH]; int alo[4], blo[NBCH];
; #pragma unroll
;   for (int i = 0; i < 4; ++i) {
;     const int c = tid + 256 * i, row = c >> 3, kc = c & 7;
;     int m = m0 + row; m = m < Mmax ? m : Mmax - 1;
;     ap[i] = A + rowA(m) + kc * 8; alo[i] = row * 144 + kc * 16;
;   }
; #pragma unroll
;   for (int i = 0; i < NBCH; ++i) {
;     const int c = tid + 256 * i, row = c >> 3, kc = c & 7;
;     bp[i] = Bt + (size_t)(n0 + row) * ldb + kc * 8; blo[i] = 128 * 144 + row * 144 + kc * 16;
;   }
;     ...
;   for (int kt = 0; kt < nk; kt += 2) {
;     G_LOAD(x0, 0, (kt + 2 < nk ? kt + 2 : nk - 1));
;     G_COMPUTE(0);
;     G_STORE(1, x1, 0);
;     __syncthreads();
;     G_LOAD(x1, 0, (kt + 3 < nk ? kt + 3 : nk - 1));
;     G_COMPUTE(1);
;     G_STORE(0, x0, 0);
;     __syncthreads();
;   }
.Lpeel_tail_19:
	ds_read_b128 v[176:179], v0
	ds_read_b128 v[180:183], v71 offset:18432
	ds_read_b128 v[184:187], v0 offset:4608
	s_add_i32 s5, s4, 4
	s_min_u32 s5, s5, 15
	s_lshl_b32 s14, s5, 7
	v_lshl_add_u64 v[78:79], v[58:59], 0, s[14:15]
	v_lshl_add_u64 v[82:83], v[60:61], 0, s[14:15]
	v_lshl_add_u64 v[86:87], v[62:63], 0, s[14:15]
	v_lshl_add_u64 v[122:123], v[64:65], 0, s[14:15]
	v_lshl_add_u64 v[126:127], v[66:67], 0, s[14:15]
	v_lshl_add_u64 v[130:131], v[68:69], 0, s[14:15]
	s_add_i32 s4, s4, 2
	s_setprio 1
	ds_read_b128 v[188:191], v0 offset:32
	ds_read_b128 v[192:195], v71 offset:18464
	ds_read_b128 v[196:199], v0 offset:4640
	s_waitcnt lgkmcnt(3)
	v_mfma_f32_32x32x16_bf16 v[18:33], v[176:179], v[180:183], v[18:33]
	v_mfma_f32_32x32x16_bf16 v[2:17], v[184:187], v[180:183], v[2:17]
	ds_read_b128 v[176:179], v0 offset:64
	ds_read_b128 v[180:183], v71 offset:18496
	ds_read_b128 v[184:187], v0 offset:4672
	s_waitcnt lgkmcnt(3)
	v_mfma_f32_32x32x16_bf16 v[18:33], v[188:191], v[192:195], v[18:33]
	v_mfma_f32_32x32x16_bf16 v[2:17], v[196:199], v[192:195], v[2:17]
	ds_read_b128 v[188:191], v0 offset:96
	ds_read_b128 v[192:195], v71 offset:18528
	ds_read_b128 v[196:199], v0 offset:4704
	s_waitcnt lgkmcnt(3)
	v_mfma_f32_32x32x16_bf16 v[18:33], v[176:179], v[180:183], v[18:33]
	s_waitcnt vmcnt(0)
	ds_write_b128 v70, v[34:37] offset:27648
	ds_write_b128 v72, v[38:41] offset:27648
	v_mfma_f32_32x32x16_bf16 v[2:17], v[184:187], v[180:183], v[2:17]
	ds_write_b128 v74, v[42:45] offset:27648
	s_waitcnt lgkmcnt(3)
	v_mfma_f32_32x32x16_bf16 v[18:33], v[188:191], v[192:195], v[18:33]
	ds_write_b128 v76, v[54:57] offset:27648
	ds_write_b128 v70, v[46:49] offset:46080
	v_mfma_f32_32x32x16_bf16 v[2:17], v[196:199], v[192:195], v[2:17]
	ds_write_b128 v72, v[50:53] offset:46080
	s_setprio 0
	s_min_u32 s5, s4, 12
	s_lshl_b32 s14, s5, 7
	v_lshl_add_u64 v[34:35], v[58:59], 0, s[14:15]
	v_lshl_add_u64 v[38:39], v[60:61], 0, s[14:15]
	v_lshl_add_u64 v[42:43], v[62:63], 0, s[14:15]
	v_lshl_add_u64 v[46:47], v[64:65], 0, s[14:15]
	v_lshl_add_u64 v[48:49], v[66:67], 0, s[14:15]
	v_lshl_add_u64 v[50:51], v[68:69], 0, s[14:15]
	s_waitcnt lgkmcnt(0)
	s_barrier
	ds_read_b128 v[176:179], v0 offset:27648
	ds_read_b128 v[180:183], v71 offset:46080
	ds_read_b128 v[184:187], v0 offset:32256
	s_setprio 1
	ds_read_b128 v[188:191], v0 offset:27680
	ds_read_b128 v[192:195], v71 offset:46112
	ds_read_b128 v[196:199], v0 offset:32288
	s_waitcnt lgkmcnt(3)
	v_mfma_f32_32x32x16_bf16 v[18:33], v[176:179], v[180:183], v[18:33]
	s_cmp_lt_u32 s4, 14
	v_mfma_f32_32x32x16_bf16 v[2:17], v[184:187], v[180:183], v[2:17]
	ds_read_b128 v[176:179], v0 offset:27712
	ds_read_b128 v[180:183], v71 offset:46144
	ds_read_b128 v[184:187], v0 offset:32320
	s_waitcnt lgkmcnt(3)
	v_mfma_f32_32x32x16_bf16 v[18:33], v[188:191], v[192:195], v[18:33]
	v_mfma_f32_32x32x16_bf16 v[2:17], v[196:199], v[192:195], v[2:17]
	ds_read_b128 v[188:191], v0 offset:27744
	ds_read_b128 v[192:195], v71 offset:46176
	ds_read_b128 v[196:199], v0 offset:32352
	s_waitcnt lgkmcnt(3)
	v_mfma_f32_32x32x16_bf16 v[18:33], v[176:179], v[180:183], v[18:33]
	v_mfma_f32_32x32x16_bf16 v[2:17], v[184:187], v[180:183], v[2:17]
	s_waitcnt lgkmcnt(0)
	v_mfma_f32_32x32x16_bf16 v[18:33], v[188:191], v[192:195], v[18:33]
	v_mfma_f32_32x32x16_bf16 v[2:17], v[196:199], v[192:195], v[2:17]
	s_setprio 0
	s_waitcnt lgkmcnt(0)
	s_barrier
	s_cmp_eq_u32 s3, 1
	s_cselect_b32 s5, s42, 0x300
	s_cselect_b32 s4, 8, 4
	s_cmp_lg_u32 s3, 0
	v_mov_b32_e32 v58, v230
	s_cselect_b32 s5, s5, 0
	v_readlane_b32 s16, v252, 57
	s_lshl_b32 s5, s5, 1
	v_ashrrev_i32_e32 v59, 3, v58
	v_readlane_b32 s28, v253, 5
	s_waitcnt vmcnt(5)
	v_add_u32_e32 v36, s1, v59
	v_readlane_b32 s29, v253, 6
	s_add_u32 s6, s28, s5
	v_lshlrev_b32_e32 v0, 4, v58
	v_min_i32_e32 v36, 0x7fff, v36
	s_addc_u32 s7, s29, 0
	v_and_b32_e32 v0, 0x70, v0
	v_ashrrev_i32_e32 v37, 31, v36
	v_lshl_add_u64 v[34:35], s[6:7], 0, v[0:1]
	v_lshlrev_b64 v[36:37], 11, v[36:37]
	v_lshl_add_u64 v[122:123], v[34:35], 0, v[36:37]
	v_add_u32_e32 v36, 0x100, v58
	v_ashrrev_i32_e32 v60, 3, v36
	v_add_u32_e32 v36, s1, v60
	v_min_i32_e32 v36, 0x7fff, v36
	v_ashrrev_i32_e32 v37, 31, v36
	v_lshlrev_b64 v[36:37], 11, v[36:37]
	v_lshl_add_u64 v[124:125], v[34:35], 0, v[36:37]
	v_add_u32_e32 v36, 0x200, v58
	v_ashrrev_i32_e32 v61, 3, v36
	v_add_u32_e32 v36, s1, v61
	v_min_i32_e32 v36, 0x7fff, v36
	v_ashrrev_i32_e32 v37, 31, v36
	v_lshlrev_b64 v[36:37], 11, v[36:37]
	v_lshl_add_u64 v[126:127], v[34:35], 0, v[36:37]
	v_add_u32_e32 v36, 0x300, v58
	v_ashrrev_i32_e32 v62, 3, v36
	v_add_u32_e32 v36, s1, v62
	v_min_i32_e32 v36, 0x7fff, v36
	v_ashrrev_i32_e32 v37, 31, v36
	v_lshlrev_b64 v[36:37], 11, v[36:37]
	v_readlane_b32 s17, v252, 58
	s_add_u32 s8, s16, s5
	v_lshl_add_u64 v[128:129], v[34:35], 0, v[36:37]
	v_add_u32_e32 v36, s2, v59
	s_addc_u32 s9, s17, 0
	v_ashrrev_i32_e32 v37, 31, v36
	v_lshl_add_u64 v[34:35], s[8:9], 0, v[0:1]
	v_lshlrev_b64 v[36:37], 11, v[36:37]
	v_lshl_add_u64 v[130:131], v[34:35], 0, v[36:37]
	v_add_u32_e32 v36, s2, v60
	v_ashrrev_i32_e32 v37, 31, v36
	v_lshlrev_b64 v[36:37], 11, v[36:37]
	v_lshl_add_u64 v[132:133], v[34:35], 0, v[36:37]
	s_barrier
; #define G_STORE(ST, S, unused) do { char* d_ = smem + (ST) * STAGE; \
;     *(uint4*)(d_ + alo[0]) = S##a0; *(uint4*)(d_ + alo[1]) = S##a1; *(uint4*)(d_ + alo[2]) = S##a2; *(uint4*)(d_ + alo[3]) = S##a3; \
;     *(uint4*)(d_ + blo[0]) = S##b0; *(uint4*)(d_ + blo[1]) = S##b1; \
;     if (NBCH == 4) { *(uint4*)(d_ + blo[NBCH - 2]) = S##b2; *(uint4*)(d_ + blo[NBCH - 1]) = S##b3; } } while (0)
; template <int NJ, class RowA>
; DI void gemm_main(f32x16 (&acc)[2][NJ], const bf16_t* __restrict__ A, RowA rowA, size_t kstrideA, int m0, int Mmax,
;                   const bf16_t* __restrict__ Bt, size_t ldb, int n0, int nk, char* smem) {
;     ...
; #pragma unroll
;   for (int i = 0; i < 2; ++i)
; #pragma unroll
;     for (int j = 0; j < NJ; ++j)
; #pragma unroll
;       for (int e = 0; e < 16; ++e) acc[i][j][e] = 0.f;
;   uint4 x0a0, x0a1, x0a2, x0a3, x0b0, x0b1, x0b2, x0b3, x1a0, x1a1, x1a2, x1a3, x1b0, x1b1, x1b2, x1b3;
;   x0b2 = x0b3 = x1b2 = x1b3 = make_uint4(0, 0, 0, 0);
;     ...
;   __syncthreads();
;   G_LOAD(x0, 0, 0);
;   G_LOAD(x1, 0, 1);
;   G_STORE(0, x0, 0);
;   __syncthreads();
; #pragma unroll 1
;   for (int kt = 0; kt < nk; kt += 2) {
;     G_LOAD(x0, 0, (kt + 2 < nk ? kt + 2 : nk - 1));
;     G_COMPUTE(0);
;     G_STORE(1, x1, 0);
;     __syncthreads();
;     G_LOAD(x1, 0, (kt + 3 < nk ? kt + 3 : nk - 1));
;     G_COMPUTE(1);
;     G_STORE(0, x0, 0);
;     __syncthreads();
;   }
	global_load_dwordx4 v[34:37], v[122:123], off
	global_load_dwordx4 v[38:41], v[124:125], off
	global_load_dwordx4 v[42:45], v[126:127], off
	global_load_dwordx4 v[46:49], v[128:129], off
	global_load_dwordx4 v[50:53], v[130:131], off
	global_load_dwordx4 v[54:57], v[132:133], off
	global_load_dwordx4 v[66:69], v[122:123], off offset:128
	global_load_dwordx4 v[70:73], v[124:125], off offset:128
	global_load_dwordx4 v[74:77], v[126:127], off offset:128
	global_load_dwordx4 v[78:81], v[128:129], off offset:128
	global_load_dwordx4 v[82:85], v[130:131], off offset:128
	global_load_dwordx4 v[86:89], v[132:133], off offset:128
	v_and_b32_e32 v63, 31, v58
	v_lshrrev_b32_e32 v58, 1, v58
	v_and_or_b32 v64, v58, s47, v63
	v_and_b32_e32 v65, 16, v58
	v_and_or_b32 v58, v58, 32, v63
	v_mad_u64_u32 v[134:135], s[6:7], v59, s76, v[0:1]
	v_mad_u64_u32 v[136:137], s[6:7], v60, s76, v[0:1]
	v_mad_u64_u32 v[138:139], s[6:7], v61, s76, v[0:1]
	v_mad_u64_u32 v[140:141], s[6:7], v62, s76, v[0:1]
	v_mul_u32_u24_e32 v58, 0x90, v58
	v_mul_lo_u32 v0, v64, s76
	s_mov_b32 s5, 3
	s_add_i32 s6, s4, -1
	v_add_u32_e32 v0, v65, v0
	v_add_u32_e32 v135, v58, v65
	v_readlane_b32 s18, v252, 59
	v_readlane_b32 s19, v252, 60
	v_readlane_b32 s20, v252, 61
	v_readlane_b32 s21, v252, 62
	v_readlane_b32 s22, v252, 63
	v_readlane_b32 s23, v253, 0
	v_readlane_b32 s24, v253, 1
	v_readlane_b32 s25, v253, 2
	v_readlane_b32 s26, v253, 3
	v_readlane_b32 s27, v253, 4
	v_readlane_b32 s30, v253, 7
	v_readlane_b32 s31, v253, 8
	s_waitcnt vmcnt(11)
	ds_write_b128 v134, v[34:37]
	s_waitcnt vmcnt(10)
	ds_write_b128 v136, v[38:41]
	s_waitcnt vmcnt(9)
	ds_write_b128 v138, v[42:45]
	s_waitcnt vmcnt(8)
	ds_write_b128 v140, v[46:49]
	s_waitcnt vmcnt(7)
	ds_write_b128 v134, v[50:53] offset:18432
	s_waitcnt vmcnt(6)
	ds_write_b128 v136, v[54:57] offset:18432
	v_mov_b32_e32 v34, 0
	v_mov_b32_e32 v35, v34
	v_mov_b32_e32 v36, v34
	v_mov_b32_e32 v37, v34
	v_mov_b32_e32 v38, v34
	v_mov_b32_e32 v39, v34
	v_mov_b32_e32 v40, v34
	v_mov_b32_e32 v41, v34
	v_mov_b32_e32 v42, v34
	v_mov_b32_e32 v43, v34
	v_mov_b32_e32 v44, v34
	v_mov_b32_e32 v45, v34
	v_mov_b32_e32 v46, v34
	v_mov_b32_e32 v47, v34
	v_mov_b32_e32 v48, v34
	v_mov_b32_e32 v49, v34
	v_mov_b32_e32 v50, v34
	v_mov_b32_e32 v51, v34
	v_mov_b32_e32 v52, v34
	v_mov_b32_e32 v53, v34
	v_mov_b32_e32 v54, v34
	v_mov_b32_e32 v55, v34
	v_mov_b32_e32 v56, v34
	v_mov_b32_e32 v57, v34
	v_mov_b32_e32 v58, v34
	v_mov_b32_e32 v59, v34
	v_mov_b32_e32 v60, v34
	v_mov_b32_e32 v61, v34
	v_mov_b32_e32 v62, v34
	v_mov_b32_e32 v63, v34
	v_mov_b32_e32 v64, v34
	v_mov_b32_e32 v65, v34
	s_waitcnt lgkmcnt(0)
	s_barrier
.LBB0_21:
	s_add_i32 s7, s5, -1
	s_cmp_lt_u32 s7, s4
	s_cbranch_scc0 .Lpeel_tail_21
	ds_read_b128 v[176:179], v0
	ds_read_b128 v[180:183], v135 offset:18432
	ds_read_b128 v[184:187], v0 offset:4608
	s_add_i32 s7, s5, -1
	s_min_u32 s14, s7, s6
	s_lshl_b64 s[8:9], s[14:15], 7
	v_lshl_add_u64 v[144:145], v[122:123], 0, s[8:9]
	v_lshl_add_u64 v[148:149], v[124:125], 0, s[8:9]
	v_lshl_add_u64 v[152:153], v[126:127], 0, s[8:9]
	v_lshl_add_u64 v[156:157], v[128:129], 0, s[8:9]
	v_lshl_add_u64 v[160:161], v[130:131], 0, s[8:9]
	v_lshl_add_u64 v[164:165], v[132:133], 0, s[8:9]
	s_setprio 1
	ds_read_b128 v[188:191], v0 offset:32
	ds_read_b128 v[192:195], v135 offset:18464
	ds_read_b128 v[196:199], v0 offset:4640
	s_waitcnt lgkmcnt(3)
	v_mfma_f32_32x32x16_bf16 v[50:65], v[176:179], v[180:183], v[50:65]
	global_load_dwordx4 v[144:147], v[144:145], off
	s_nop 0
	global_load_dwordx4 v[148:151], v[148:149], off
	v_mfma_f32_32x32x16_bf16 v[34:49], v[184:187], v[180:183], v[34:49]
	global_load_dwordx4 v[152:155], v[152:153], off
	ds_read_b128 v[176:179], v0 offset:64
	ds_read_b128 v[180:183], v135 offset:18496
	ds_read_b128 v[184:187], v0 offset:4672
	s_waitcnt lgkmcnt(3)
	v_mfma_f32_32x32x16_bf16 v[50:65], v[188:191], v[192:195], v[50:65]
	global_load_dwordx4 v[156:159], v[156:157], off
	s_nop 0
	global_load_dwordx4 v[160:163], v[160:161], off
	s_waitcnt vmcnt(5)
	ds_write_b128 v134, v[66:69] offset:27648
	ds_write_b128 v136, v[70:73] offset:27648
	v_mfma_f32_32x32x16_bf16 v[34:49], v[196:199], v[192:195], v[34:49]
	global_load_dwordx4 v[164:167], v[164:165], off
	ds_write_b128 v138, v[74:77] offset:27648
	ds_read_b128 v[188:191], v0 offset:96
	ds_read_b128 v[192:195], v135 offset:18528
	ds_read_b128 v[196:199], v0 offset:4704
	s_waitcnt lgkmcnt(6)
	v_mfma_f32_32x32x16_bf16 v[50:65], v[176:179], v[180:183], v[50:65]
	ds_write_b128 v140, v[78:81] offset:27648
	ds_write_b128 v134, v[82:85] offset:46080
	v_mfma_f32_32x32x16_bf16 v[34:49], v[184:187], v[180:183], v[34:49]
	ds_write_b128 v136, v[86:89] offset:46080
	s_waitcnt lgkmcnt(3)
	v_mfma_f32_32x32x16_bf16 v[50:65], v[188:191], v[192:195], v[50:65]
	s_min_u32 s14, s5, s6
	s_lshl_b64 s[8:9], s[14:15], 7
	v_lshl_add_u64 v[66:67], v[122:123], 0, s[8:9]
	v_lshl_add_u64 v[70:71], v[124:125], 0, s[8:9]
	v_mfma_f32_32x32x16_bf16 v[34:49], v[196:199], v[192:195], v[34:49]
	v_lshl_add_u64 v[74:75], v[126:127], 0, s[8:9]
	v_lshl_add_u64 v[78:79], v[128:129], 0, s[8:9]
	v_lshl_add_u64 v[82:83], v[130:131], 0, s[8:9]
	v_lshl_add_u64 v[86:87], v[132:133], 0, s[8:9]
	s_setprio 0
	s_waitcnt lgkmcnt(0)
	s_barrier
	ds_read_b128 v[176:179], v0 offset:27648
	ds_read_b128 v[180:183], v135 offset:46080
	ds_read_b128 v[184:187], v0 offset:32256
	s_setprio 1
	ds_read_b128 v[188:191], v0 offset:27680
	ds_read_b128 v[192:195], v135 offset:46112
	ds_read_b128 v[196:199], v0 offset:32288
	s_waitcnt lgkmcnt(3)
	v_mfma_f32_32x32x16_bf16 v[50:65], v[176:179], v[180:183], v[50:65]
	global_load_dwordx4 v[66:69], v[66:67], off
	s_nop 0
	global_load_dwordx4 v[70:73], v[70:71], off
	v_mfma_f32_32x32x16_bf16 v[34:49], v[184:187], v[180:183], v[34:49]
	global_load_dwordx4 v[74:77], v[74:75], off
	ds_read_b128 v[176:179], v0 offset:27712
	ds_read_b128 v[180:183], v135 offset:46144
	ds_read_b128 v[184:187], v0 offset:32320
	s_waitcnt lgkmcnt(3)
	v_mfma_f32_32x32x16_bf16 v[50:65], v[188:191], v[192:195], v[50:65]
	global_load_dwordx4 v[78:81], v[78:79], off
	s_nop 0
	global_load_dwordx4 v[82:85], v[82:83], off
	s_waitcnt vmcnt(5)
	ds_write_b128 v134, v[144:147]
	ds_write_b128 v136, v[148:151]
	v_mfma_f32_32x32x16_bf16 v[34:49], v[196:199], v[192:195], v[34:49]
	global_load_dwordx4 v[86:89], v[86:87], off
	ds_write_b128 v138, v[152:155]
	ds_read_b128 v[188:191], v0 offset:27744
	ds_read_b128 v[192:195], v135 offset:46176
	ds_read_b128 v[196:199], v0 offset:32352
	s_waitcnt lgkmcnt(6)
	v_mfma_f32_32x32x16_bf16 v[50:65], v[176:179], v[180:183], v[50:65]
	ds_write_b128 v140, v[156:159]
	ds_write_b128 v134, v[160:163] offset:18432
	v_mfma_f32_32x32x16_bf16 v[34:49], v[184:187], v[180:183], v[34:49]
	ds_write_b128 v136, v[164:167] offset:18432
	s_waitcnt lgkmcnt(3)
	v_mfma_f32_32x32x16_bf16 v[50:65], v[188:191], v[192:195], v[50:65]
	s_add_i32 s5, s5, 2
	v_mfma_f32_32x32x16_bf16 v[34:49], v[196:199], v[192:195], v[34:49]
	s_cmp_lt_u32 s7, s4
	s_setprio 0
	s_waitcnt lgkmcnt(0)
	s_barrier
	s_branch .LBB0_21
; DI float sigmoidf(float x) { return __builtin_amdgcn_rcpf(1.f + __expf(-x)); }
; #define G_STORE(ST, S, unused) do { char* d_ = smem + (ST) * STAGE; \
;     *(uint4*)(d_ + alo[0]) = S##a0; *(uint4*)(d_ + alo[1]) = S##a1; *(uint4*)(d_ + alo[2]) = S##a2; *(uint4*)(d_ + alo[3]) = S##a3; \
;     *(uint4*)(d_ + blo[0]) = S##b0; *(uint4*)(d_ + blo[1]) = S##b1; \
;     if (NBCH == 4) { *(uint4*)(d_ + blo[NBCH - 2]) = S##b2; *(uint4*)(d_ + blo[NBCH - 1]) = S##b3; } } while (0)
; template <int NJ, class RowA>
; DI void gemm_main(f32x16 (&acc)[2][NJ], const bf16_t* __restrict__ A, RowA rowA, size_t kstrideA, int m0, int Mmax,
;                   const bf16_t* __restrict__ Bt, size_t ldb, int n0, int nk, char* smem) {
;     ...
;   for (int kt = 0; kt < nk; kt += 2) {
;     G_LOAD(x0, 0, (kt + 2 < nk ? kt + 2 : nk - 1));
;     G_COMPUTE(0);
;     G_STORE(1, x1, 0);
;     __syncthreads();
;     G_LOAD(x1, 0, (kt + 3 < nk ? kt + 3 : nk - 1));
;     G_COMPUTE(1);
;     G_STORE(0, x0, 0);
;     __syncthreads();
;   }
; DI void merge_tile(const Params& p, int mt, int nt, char* smem) {
;     ...
;     for (int i = 0; i < 2; ++i)
; #pragma unroll
;       for (int e = 0; e < 16; ++e) mac[i][0][e] += sigmoidf(ag[i][0][e]) * ap[i][0][e];
.Lpeel_tail_21:
	ds_read_b128 v[176:179], v0
	ds_read_b128 v[180:183], v135 offset:18432
	ds_read_b128 v[184:187], v0 offset:4608
	s_add_i32 s7, s5, -1
	s_min_u32 s14, s7, s6
	s_lshl_b64 s[8:9], s[14:15], 7
	v_lshl_add_u64 v[144:145], v[122:123], 0, s[8:9]
	v_lshl_add_u64 v[148:149], v[124:125], 0, s[8:9]
	v_lshl_add_u64 v[152:153], v[126:127], 0, s[8:9]
	v_lshl_add_u64 v[156:157], v[128:129], 0, s[8:9]
	v_lshl_add_u64 v[160:161], v[130:131], 0, s[8:9]
	v_lshl_add_u64 v[164:165], v[132:133], 0, s[8:9]
	s_setprio 1
	ds_read_b128 v[188:191], v0 offset:32
	ds_read_b128 v[192:195], v135 offset:18464
	ds_read_b128 v[196:199], v0 offset:4640
	s_waitcnt lgkmcnt(3)
	v_mfma_f32_32x32x16_bf16 v[50:65], v[176:179], v[180:183], v[50:65]
	v_mfma_f32_32x32x16_bf16 v[34:49], v[184:187], v[180:183], v[34:49]
	ds_read_b128 v[176:179], v0 offset:64
	ds_read_b128 v[180:183], v135 offset:18496
	ds_read_b128 v[184:187], v0 offset:4672
	s_waitcnt lgkmcnt(3)
	v_mfma_f32_32x32x16_bf16 v[50:65], v[188:191], v[192:195], v[50:65]
	v_mfma_f32_32x32x16_bf16 v[34:49], v[196:199], v[192:195], v[34:49]
	ds_read_b128 v[188:191], v0 offset:96
	ds_read_b128 v[192:195], v135 offset:18528
	ds_read_b128 v[196:199], v0 offset:4704
	s_waitcnt lgkmcnt(3)
	v_mfma_f32_32x32x16_bf16 v[50:65], v[176:179], v[180:183], v[50:65]
	s_waitcnt vmcnt(0)
	ds_write_b128 v134, v[66:69] offset:27648
	ds_write_b128 v136, v[70:73] offset:27648
	v_mfma_f32_32x32x16_bf16 v[34:49], v[184:187], v[180:183], v[34:49]
	ds_write_b128 v138, v[74:77] offset:27648
	s_waitcnt lgkmcnt(3)
	v_mfma_f32_32x32x16_bf16 v[50:65], v[188:191], v[192:195], v[50:65]
	ds_write_b128 v140, v[78:81] offset:27648
	ds_write_b128 v134, v[82:85] offset:46080
	v_mfma_f32_32x32x16_bf16 v[34:49], v[196:199], v[192:195], v[34:49]
	ds_write_b128 v136, v[86:89] offset:46080
	s_setprio 0
	s_min_u32 s14, s5, s6
	s_lshl_b64 s[8:9], s[14:15], 7
	v_lshl_add_u64 v[66:67], v[122:123], 0, s[8:9]
	v_lshl_add_u64 v[70:71], v[124:125], 0, s[8:9]
	v_lshl_add_u64 v[74:75], v[126:127], 0, s[8:9]
	v_lshl_add_u64 v[78:79], v[128:129], 0, s[8:9]
	v_lshl_add_u64 v[82:83], v[130:131], 0, s[8:9]
	v_lshl_add_u64 v[86:87], v[132:133], 0, s[8:9]
	s_waitcnt lgkmcnt(0)
	s_barrier
	ds_read_b128 v[176:179], v0 offset:27648
	ds_read_b128 v[180:183], v135 offset:46080
	ds_read_b128 v[184:187], v0 offset:32256
	s_setprio 1
	ds_read_b128 v[188:191], v0 offset:27680
	ds_read_b128 v[192:195], v135 offset:46112
	ds_read_b128 v[196:199], v0 offset:32288
	s_waitcnt lgkmcnt(3)
	v_mfma_f32_32x32x16_bf16 v[50:65], v[176:179], v[180:183], v[50:65]
	s_add_i32 s5, s5, 2
	v_mfma_f32_32x32x16_bf16 v[34:49], v[184:187], v[180:183], v[34:49]
	s_cmp_lt_u32 s7, s4
	ds_read_b128 v[176:179], v0 offset:27712
	ds_read_b128 v[180:183], v135 offset:46144
	ds_read_b128 v[184:187], v0 offset:32320
	s_waitcnt lgkmcnt(3)
	v_mfma_f32_32x32x16_bf16 v[50:65], v[188:191], v[192:195], v[50:65]
	v_mfma_f32_32x32x16_bf16 v[34:49], v[196:199], v[192:195], v[34:49]
	ds_read_b128 v[188:191], v0 offset:27744
	ds_read_b128 v[192:195], v135 offset:46176
	ds_read_b128 v[196:199], v0 offset:32352
	s_waitcnt lgkmcnt(3)
	v_mfma_f32_32x32x16_bf16 v[50:65], v[176:179], v[180:183], v[50:65]
	v_mfma_f32_32x32x16_bf16 v[34:49], v[184:187], v[180:183], v[34:49]
	s_waitcnt lgkmcnt(0)
	v_mfma_f32_32x32x16_bf16 v[50:65], v[188:191], v[192:195], v[50:65]
	v_mfma_f32_32x32x16_bf16 v[34:49], v[196:199], v[192:195], v[34:49]
	s_setprio 0
	s_waitcnt lgkmcnt(0)
	s_barrier
	v_mul_f32_e32 v0, 0xbfb8aa3b, v18
	v_exp_f32_e32 v0, v0
	v_mul_f32_e32 v18, 0xbfb8aa3b, v19
	v_exp_f32_e32 v18, v18
	s_add_i32 s3, s3, 1
	v_add_f32_e32 v0, 1.0, v0
	s_cmp_lg_u32 s3, 3
	v_add_f32_e32 v19, 1.0, v18
	v_rcp_f32_e32 v18, v0
	v_mul_f32_e32 v0, 0xbfb8aa3b, v20
	v_exp_f32_e32 v0, v0
	v_mul_f32_e32 v20, 0xbfb8aa3b, v21
	v_rcp_f32_e32 v19, v19
	v_exp_f32_e32 v20, v20
	v_add_f32_e32 v0, 1.0, v0
	v_pk_fma_f32 v[120:121], v[18:19], v[50:51], v[120:121]
	v_rcp_f32_e32 v18, v0
	v_add_f32_e32 v0, 1.0, v20
	v_rcp_f32_e32 v19, v0
	v_mul_f32_e32 v0, 0xbfb8aa3b, v22
	v_exp_f32_e32 v0, v0
	v_mul_f32_e32 v20, 0xbfb8aa3b, v23
	v_exp_f32_e32 v20, v20
	v_pk_fma_f32 v[118:119], v[18:19], v[52:53], v[118:119]
	v_add_f32_e32 v0, 1.0, v0
	v_rcp_f32_e32 v18, v0
	v_add_f32_e32 v0, 1.0, v20
	v_rcp_f32_e32 v19, v0
	v_mul_f32_e32 v0, 0xbfb8aa3b, v24
	v_exp_f32_e32 v0, v0
	v_mul_f32_e32 v20, 0xbfb8aa3b, v25
	v_exp_f32_e32 v20, v20
	v_pk_fma_f32 v[116:117], v[18:19], v[54:55], v[116:117]
	v_add_f32_e32 v0, 1.0, v0
	v_rcp_f32_e32 v18, v0
	v_add_f32_e32 v0, 1.0, v20
	v_rcp_f32_e32 v19, v0
	v_mul_f32_e32 v0, 0xbfb8aa3b, v26
	v_exp_f32_e32 v0, v0
	v_mul_f32_e32 v20, 0xbfb8aa3b, v27
	v_exp_f32_e32 v20, v20
	v_pk_fma_f32 v[114:115], v[18:19], v[56:57], v[114:115]
	v_add_f32_e32 v0, 1.0, v0
	v_rcp_f32_e32 v18, v0
	v_add_f32_e32 v0, 1.0, v20
	v_rcp_f32_e32 v19, v0
	v_mul_f32_e32 v0, 0xbfb8aa3b, v28
	v_exp_f32_e32 v0, v0
	v_mul_f32_e32 v20, 0xbfb8aa3b, v29
	v_exp_f32_e32 v20, v20
	v_pk_fma_f32 v[112:113], v[18:19], v[58:59], v[112:113]
	v_add_f32_e32 v0, 1.0, v0
	v_rcp_f32_e32 v18, v0
	v_add_f32_e32 v0, 1.0, v20
	v_rcp_f32_e32 v19, v0
	v_mul_f32_e32 v0, 0xbfb8aa3b, v30
	v_exp_f32_e32 v0, v0
	v_mul_f32_e32 v20, 0xbfb8aa3b, v31
	v_exp_f32_e32 v20, v20
	v_pk_fma_f32 v[110:111], v[18:19], v[60:61], v[110:111]
	v_add_f32_e32 v0, 1.0, v0
	v_rcp_f32_e32 v18, v0
	v_add_f32_e32 v0, 1.0, v20
	v_rcp_f32_e32 v19, v0
	v_mul_f32_e32 v0, 0xbfb8aa3b, v32
	v_exp_f32_e32 v0, v0
	v_mul_f32_e32 v20, 0xbfb8aa3b, v33
	v_exp_f32_e32 v20, v20
	v_pk_fma_f32 v[108:109], v[18:19], v[62:63], v[108:109]
	v_add_f32_e32 v0, 1.0, v0
	v_rcp_f32_e32 v18, v0
	v_add_f32_e32 v0, 1.0, v20
	v_rcp_f32_e32 v19, v0
; #define TIDX (tid_launder())
; DI int crow(int reg, int hh) { return (reg & 3) + 8 * (reg >> 2) + 4 * hh; }
; DI float sigmoidf(float x) { return __builtin_amdgcn_rcpf(1.f + __expf(-x)); }
; template <int NJ>
; DI void acc_to_ct(const f32x16 (&acc)[2][NJ], float* Ct) {
;   const int lane = TIDX & 63, wid = TIDX >> 6, wm = wid >> 1, wn = wid & 1;
;   const int r = lane & 31, hh = lane >> 5;
; #pragma unroll
;   for (int i = 0; i < 2; ++i)
; #pragma unroll
;     for (int j = 0; j < NJ; ++j)
; #pragma unroll
;       for (int e = 0; e < 16; ++e) Ct[(wm * 64 + i * 32 + crow(e, hh)) * 132 + wn * 32 * NJ + j * 32 + r] = acc[i][j][e];
;   __syncthreads();
; DI void merge_tile(const Params& p, int mt, int nt, char* smem) {
;     ...
;     for (int i = 0; i < 2; ++i)
; #pragma unroll
;       for (int e = 0; e < 16; ++e) mac[i][0][e] += sigmoidf(ag[i][0][e]) * ap[i][0][e];
;   }
;   float* Ct = (float*)smem;
;   acc_to_ct<1>(mac, Ct);
	v_mul_f32_e32 v0, 0xbfb8aa3b, v2
	v_exp_f32_e32 v0, v0
	v_mul_f32_e32 v2, 0xbfb8aa3b, v3
	v_exp_f32_e32 v3, v2
	v_pk_fma_f32 v[106:107], v[18:19], v[64:65], v[106:107]
	v_add_f32_e32 v0, 1.0, v0
	v_rcp_f32_e32 v2, v0
	v_add_f32_e32 v0, 1.0, v3
	v_rcp_f32_e32 v3, v0
	v_mul_f32_e32 v0, 0xbfb8aa3b, v4
	v_exp_f32_e32 v0, v0
	v_mul_f32_e32 v4, 0xbfb8aa3b, v5
	v_exp_f32_e32 v4, v4
	v_pk_fma_f32 v[104:105], v[2:3], v[34:35], v[104:105]
	v_add_f32_e32 v0, 1.0, v0
	v_rcp_f32_e32 v2, v0
	v_add_f32_e32 v0, 1.0, v4
	v_rcp_f32_e32 v3, v0
	v_mul_f32_e32 v0, 0xbfb8aa3b, v6
	v_exp_f32_e32 v0, v0
	v_mul_f32_e32 v4, 0xbfb8aa3b, v7
	v_exp_f32_e32 v4, v4
	v_pk_fma_f32 v[102:103], v[2:3], v[36:37], v[102:103]
	v_add_f32_e32 v0, 1.0, v0
	v_rcp_f32_e32 v2, v0
	v_add_f32_e32 v0, 1.0, v4
	v_rcp_f32_e32 v3, v0
	v_mul_f32_e32 v0, 0xbfb8aa3b, v8
	v_exp_f32_e32 v0, v0
	v_mul_f32_e32 v4, 0xbfb8aa3b, v9
	v_exp_f32_e32 v4, v4
	v_pk_fma_f32 v[100:101], v[2:3], v[38:39], v[100:101]
	v_add_f32_e32 v0, 1.0, v0
	v_rcp_f32_e32 v2, v0
	v_add_f32_e32 v0, 1.0, v4
	v_rcp_f32_e32 v3, v0
	v_mul_f32_e32 v0, 0xbfb8aa3b, v10
	v_exp_f32_e32 v0, v0
	v_mul_f32_e32 v4, 0xbfb8aa3b, v11
	v_exp_f32_e32 v4, v4
	v_pk_fma_f32 v[98:99], v[2:3], v[40:41], v[98:99]
	v_add_f32_e32 v0, 1.0, v0
	v_rcp_f32_e32 v2, v0
	v_add_f32_e32 v0, 1.0, v4
	v_rcp_f32_e32 v3, v0
	v_mul_f32_e32 v0, 0xbfb8aa3b, v12
	v_exp_f32_e32 v0, v0
	v_mul_f32_e32 v4, 0xbfb8aa3b, v13
	v_exp_f32_e32 v4, v4
	v_pk_fma_f32 v[96:97], v[2:3], v[42:43], v[96:97]
	v_add_f32_e32 v0, 1.0, v0
	v_rcp_f32_e32 v2, v0
	v_add_f32_e32 v0, 1.0, v4
	v_rcp_f32_e32 v3, v0
	v_mul_f32_e32 v0, 0xbfb8aa3b, v14
	v_exp_f32_e32 v0, v0
	v_mul_f32_e32 v4, 0xbfb8aa3b, v15
	v_exp_f32_e32 v4, v4
	v_pk_fma_f32 v[94:95], v[2:3], v[44:45], v[94:95]
	v_add_f32_e32 v0, 1.0, v0
	v_mul_f32_e32 v3, 0xbfb8aa3b, v16
	v_rcp_f32_e32 v2, v0
	v_add_f32_e32 v0, 1.0, v4
	v_exp_f32_e32 v4, v3
	v_mul_f32_e32 v3, 0xbfb8aa3b, v17
	v_exp_f32_e32 v5, v3
	v_rcp_f32_e32 v3, v0
	v_add_f32_e32 v0, 1.0, v4
	v_rcp_f32_e32 v4, v0
	v_add_f32_e32 v0, 1.0, v5
	v_rcp_f32_e32 v5, v0
	v_pk_fma_f32 v[92:93], v[2:3], v[46:47], v[92:93]
	v_pk_fma_f32 v[90:91], v[4:5], v[48:49], v[90:91]
	s_cbranch_scc1 .LBB0_18
	v_mov_b32_e32 v0, v230
	v_mov_b32_e32 v2, v230
	v_and_b32_e32 v3, 31, v0
	v_lshrrev_b32_e32 v0, 3, v0
	v_and_b32_e32 v0, 4, v0
	v_lshrrev_b32_e32 v4, 1, v2
	v_and_or_b32 v4, v4, s47, v0
	v_lshlrev_b32_e32 v0, 1, v2
	v_and_b32_e32 v0, 0x80, v0
	v_lshl_or_b32 v0, v3, 2, v0
	v_mad_u64_u32 v[2:3], s[4:5], v4, s79, v[0:1]
	v_add_u32_e32 v0, 0x400, v2
	ds_write2_b32 v0, v118, v119 offset0:8 offset1:140
	v_add_u32_e32 v0, 0x1000, v2
	ds_write2_b32 v0, v116, v117 offset0:32 offset1:164
	v_add_u32_e32 v0, 0x1400, v2
	ds_write2_b32 v0, v114, v115 offset0:40 offset1:172
	v_add_u32_e32 v0, 0x2000, v2
	ds_write2_b32 v0, v112, v113 offset0:64 offset1:196
	v_add_u32_e32 v0, 0x2400, v2
	ds_write2_b32 v0, v110, v111 offset0:72 offset1:204
	v_add_u32_e32 v0, 0x3000, v2
	ds_write2_b32 v0, v108, v109 offset0:96 offset1:228
	v_add_u32_e32 v0, 0x3400, v2
	ds_write2_b32 v0, v106, v107 offset0:104 offset1:236
	v_add_u32_e32 v0, 0x4200, v2
	ds_write2_b32 v0, v104, v105 offset1:132
	v_add_u32_e32 v0, 0x4600, v2
	ds_write2_b32 v0, v102, v103 offset0:8 offset1:140
	v_add_u32_e32 v0, 0x5200, v2
	ds_write2_b32 v0, v100, v101 offset0:32 offset1:164
	v_add_u32_e32 v0, 0x5600, v2
	ds_write2_b32 v0, v98, v99 offset0:40 offset1:172
	v_add_u32_e32 v0, 0x6200, v2
	ds_write2_b32 v0, v96, v97 offset0:64 offset1:196
	v_add_u32_e32 v0, 0x6600, v2
	ds_write2_b32 v0, v94, v95 offset0:72 offset1:204
	v_add_u32_e32 v0, 0x7200, v2
	ds_write2_b32 v0, v92, v93 offset0:96 offset1:228
	v_add_u32_e32 v0, 0x7600, v2
	ds_write2_b32 v0, v90, v91 offset0:104 offset1:236
	v_mov_b32_e32 v0, v230
	ds_write2_b32 v2, v120, v121 offset1:132
	s_waitcnt lgkmcnt(0)
	s_barrier
; #define TIDX (tid_launder())
; DI unsigned pack2(float a, float b) { hwf2 v = {a, b}; hwbf2 r = __builtin_convertvector(v, hwbf2); return __builtin_bit_cast(unsigned, r); }
; DI float siluf(float x) { return x * __builtin_amdgcn_rcpf(1.f + __expf(-x)); }
; DI void epi_store64(const float* Ct, int cb, const float* rn, int grp, const float* gain, bool silu, const float* bias,
;                     bf16_t* dst, size_t ldd, int dcol0, int m0, int Mmax) {
;   const int tid = TIDX, c = (tid & 15) * 4;
;   float4 gv = make_float4(1.f, 1.f, 1.f, 1.f), bv = make_float4(0.f, 0.f, 0.f, 0.f);
;   if (rn) gv = *(const float4*)(gain + c);
;   if (bias) bv = *(const float4*)(bias + c);
; #pragma unroll
;   for (int q = 0; q < 8; ++q) {
;     const int row = (tid >> 4) + 16 * q;
;     float4 v = *(const float4*)(Ct + row * 132 + cb + c);
;     v.x += bv.x; v.y += bv.y; v.z += bv.z; v.w += bv.w;
;     if (rn) { const float sc = rn[row * 2 + grp]; v.x *= sc * gv.x; v.y *= sc * gv.y; v.z *= sc * gv.z; v.w *= sc * gv.w; }
;     if (silu) { v.x = siluf(v.x); v.y = siluf(v.y); v.z = siluf(v.z); v.w = siluf(v.w); }
;     uint2 o; o.x = pack2(v.x, v.y); o.y = pack2(v.z, v.w);
;     *(uint2*)(dst + (size_t)(m0 + row) * ldd + dcol0 + c) = o;
;   }
; }
; DI void merge_tile(const Params& p, int mt, int nt, char* smem) {
;     ...
;   epi_store64(Ct, 0, nullptr, 0, nullptr, false, nullptr, p.merged, 1024, n0, m0, T_TOK);
;   __syncthreads();
	s_lshl_b32 s2, s2, 1
	v_lshlrev_b32_e32 v2, 2, v0
	v_ashrrev_i32_e32 v12, 4, v0
	v_and_b32_e32 v6, 60, v2
	v_mul_lo_u32 v0, v12, s79
	v_lshl_add_u32 v14, v6, 2, v0
	ds_read_b128 v[2:5], v14
	v_readlane_b32 s4, v250, 50
	v_lshlrev_b32_e32 v0, 1, v6
	ds_read_b128 v[6:9], v14 offset:8448
	v_readlane_b32 s5, v250, 51
	s_add_u32 s2, s4, s2
	v_add_u32_e32 v12, s1, v12
	s_addc_u32 s3, s5, 0
	s_waitcnt lgkmcnt(1)
	v_pk_add_f32 v[2:3], v[2:3], 0 op_sel_hi:[1,0]
	v_pk_add_f32 v[4:5], v[4:5], 0 op_sel_hi:[1,0]
	v_ashrrev_i32_e32 v13, 31, v12
	v_lshl_add_u64 v[10:11], s[2:3], 0, v[0:1]
	v_cvt_pk_bf16_f32 v2, v2, v3
	v_cvt_pk_bf16_f32 v3, v4, v5
	v_lshlrev_b64 v[4:5], 11, v[12:13]
	v_lshl_add_u64 v[4:5], v[10:11], 0, v[4:5]
	global_store_dwordx2 v[4:5], v[2:3], off
	s_waitcnt lgkmcnt(0)
	v_pk_add_f32 v[2:3], v[6:7], 0 op_sel_hi:[1,0]
	v_pk_add_f32 v[4:5], v[8:9], 0 op_sel_hi:[1,0]
	v_cvt_pk_bf16_f32 v6, v2, v3
	v_cvt_pk_bf16_f32 v7, v4, v5
	ds_read_b128 v[2:5], v14 offset:16896
	v_add_u32_e32 v8, 16, v12
	v_ashrrev_i32_e32 v9, 31, v8
	v_lshlrev_b64 v[8:9], 11, v[8:9]
	v_lshl_add_u64 v[8:9], v[10:11], 0, v[8:9]
	global_store_dwordx2 v[8:9], v[6:7], off
	ds_read_b128 v[6:9], v14 offset:25344
	s_waitcnt lgkmcnt(1)
	v_pk_add_f32 v[2:3], v[2:3], 0 op_sel_hi:[1,0]
	v_pk_add_f32 v[4:5], v[4:5], 0 op_sel_hi:[1,0]
	v_cvt_pk_bf16_f32 v2, v2, v3
	v_cvt_pk_bf16_f32 v3, v4, v5
	v_add_u32_e32 v4, 32, v12
	v_ashrrev_i32_e32 v5, 31, v4
	v_lshlrev_b64 v[4:5], 11, v[4:5]
	v_lshl_add_u64 v[4:5], v[10:11], 0, v[4:5]
	global_store_dwordx2 v[4:5], v[2:3], off
	s_waitcnt lgkmcnt(0)
	v_pk_add_f32 v[2:3], v[6:7], 0 op_sel_hi:[1,0]
	v_pk_add_f32 v[4:5], v[8:9], 0 op_sel_hi:[1,0]
	v_cvt_pk_bf16_f32 v6, v2, v3
	v_cvt_pk_bf16_f32 v7, v4, v5
	ds_read_b128 v[2:5], v14 offset:33792
	v_add_u32_e32 v8, 48, v12
	v_ashrrev_i32_e32 v9, 31, v8
	v_lshlrev_b64 v[8:9], 11, v[8:9]
	v_lshl_add_u64 v[8:9], v[10:11], 0, v[8:9]
	global_store_dwordx2 v[8:9], v[6:7], off
	ds_read_b128 v[6:9], v14 offset:42240
	s_waitcnt lgkmcnt(1)
	v_pk_add_f32 v[2:3], v[2:3], 0 op_sel_hi:[1,0]
	v_pk_add_f32 v[4:5], v[4:5], 0 op_sel_hi:[1,0]
	v_cvt_pk_bf16_f32 v2, v2, v3
	v_cvt_pk_bf16_f32 v3, v4, v5
	v_add_u32_e32 v4, 64, v12
	v_ashrrev_i32_e32 v5, 31, v4
	v_lshlrev_b64 v[4:5], 11, v[4:5]
	v_lshl_add_u64 v[4:5], v[10:11], 0, v[4:5]
	global_store_dwordx2 v[4:5], v[2:3], off
	s_waitcnt lgkmcnt(0)
	v_pk_add_f32 v[2:3], v[6:7], 0 op_sel_hi:[1,0]
	v_pk_add_f32 v[4:5], v[8:9], 0 op_sel_hi:[1,0]
	v_cvt_pk_bf16_f32 v6, v2, v3
	v_cvt_pk_bf16_f32 v7, v4, v5
	ds_read_b128 v[2:5], v14 offset:50688
	v_add_u32_e32 v8, 0x50, v12
	v_ashrrev_i32_e32 v9, 31, v8
	v_lshlrev_b64 v[8:9], 11, v[8:9]
	v_lshl_add_u64 v[8:9], v[10:11], 0, v[8:9]
	global_store_dwordx2 v[8:9], v[6:7], off
	ds_read_b128 v[6:9], v14 offset:59136
	s_waitcnt lgkmcnt(1)
	v_pk_add_f32 v[2:3], v[2:3], 0 op_sel_hi:[1,0]
	v_pk_add_f32 v[4:5], v[4:5], 0 op_sel_hi:[1,0]
	v_cvt_pk_bf16_f32 v2, v2, v3
	v_cvt_pk_bf16_f32 v3, v4, v5
	v_add_u32_e32 v4, 0x60, v12
	v_ashrrev_i32_e32 v5, 31, v4
	v_lshlrev_b64 v[4:5], 11, v[4:5]
	v_lshl_add_u64 v[4:5], v[10:11], 0, v[4:5]
	global_store_dwordx2 v[4:5], v[2:3], off
	s_waitcnt lgkmcnt(0)
	v_pk_add_f32 v[2:3], v[6:7], 0 op_sel_hi:[1,0]
	v_pk_add_f32 v[4:5], v[8:9], 0 op_sel_hi:[1,0]
	v_cvt_pk_bf16_f32 v2, v2, v3
	v_cvt_pk_bf16_f32 v3, v4, v5
	v_add_u32_e32 v4, 0x70, v12
	v_ashrrev_i32_e32 v5, 31, v4
	v_readlane_b32 s1, v250, 60
	v_lshlrev_b64 v[4:5], 11, v[4:5]
	s_add_i32 s0, s0, s1
	v_lshl_add_u64 v[4:5], v[10:11], 0, v[4:5]
	s_cmpk_gt_u32 s0, 0x1ff
	v_readlane_b32 s6, v250, 52
	v_readlane_b32 s7, v250, 53
	global_store_dwordx2 v[4:5], v[2:3], off
	s_barrier
	s_cbranch_scc0 .LBB0_17

; #define G_STORE(ST, S, unused) do { char* d_ = smem + (ST) * STAGE; \
;     *(uint4*)(d_ + alo[0]) = S##a0; *(uint4*)(d_ + alo[1]) = S##a1; *(uint4*)(d_ + alo[2]) = S##a2; *(uint4*)(d_ + alo[3]) = S##a3; \
;     *(uint4*)(d_ + blo[0]) = S##b0; *(uint4*)(d_ + blo[1]) = S##b1; \
;     if (NBCH == 4) { *(uint4*)(d_ + blo[NBCH - 2]) = S##b2; *(uint4*)(d_ + blo[NBCH - 1]) = S##b3; } } while (0)
; template <int NJ, class RowA>
; DI void gemm_main(f32x16 (&acc)[2][NJ], const bf16_t* __restrict__ A, RowA rowA, size_t kstrideA, int m0, int Mmax,
;                   const bf16_t* __restrict__ Bt, size_t ldb, int n0, int nk, char* smem) {
;     ...
;   __syncthreads();
;   G_LOAD(x0, 0, 0);
;   G_LOAD(x1, 0, 1);
;   G_STORE(0, x0, 0);
;   __syncthreads();
; #pragma unroll 1
;   for (int kt = 0; kt < nk; kt += 2) {
;     G_LOAD(x0, 0, (kt + 2 < nk ? kt + 2 : nk - 1));
;     G_COMPUTE(0);
;     G_STORE(1, x1, 0);
;     __syncthreads();
;     G_LOAD(x1, 0, (kt + 3 < nk ? kt + 3 : nk - 1));
;     G_COMPUTE(1);
;     G_STORE(0, x0, 0);
;     __syncthreads();
;   }
.LBB0_1956:
	s_cmp_lt_i32 s0, 12
	s_cbranch_scc0 .Lpeel_tail_1956
	ds_read_b128 v[166:169], v0
	ds_read_b128 v[170:173], v139 offset:18432
	ds_read_b128 v[174:177], v139 offset:23040
	ds_read_b128 v[178:181], v0 offset:4608
	s_add_i32 s1, s0, 4
	s_min_u32 s1, s1, 15
	s_lshl_b32 s14, s1, 7
	v_lshl_add_u64 v[98:99], v[122:123], 0, s[14:15]
	v_lshl_add_u64 v[102:103], v[124:125], 0, s[14:15]
	v_lshl_add_u64 v[106:107], v[126:127], 0, s[14:15]
	v_lshl_add_u64 v[110:111], v[128:129], 0, s[14:15]
	v_lshl_add_u64 v[114:115], v[130:131], 0, s[14:15]
	v_lshl_add_u64 v[118:119], v[132:133], 0, s[14:15]
	s_add_i32 s0, s0, 2
	v_lshl_add_u64 v[158:159], v[134:135], 0, s[14:15]
	v_lshl_add_u64 v[160:161], v[136:137], 0, s[14:15]
	s_setprio 1
	ds_read_b128 v[182:185], v0 offset:32
	ds_read_b128 v[186:189], v139 offset:18464
	ds_read_b128 v[190:193], v139 offset:23072
	ds_read_b128 v[194:197], v0 offset:4640
	s_waitcnt lgkmcnt(4)
	v_mfma_f32_32x32x16_bf16 v[50:65], v[166:169], v[170:173], v[50:65]
	global_load_dwordx4 v[98:101], v[98:99], off
	v_mfma_f32_32x32x16_bf16 v[34:49], v[166:169], v[174:177], v[34:49]
	global_load_dwordx4 v[102:105], v[102:103], off
	v_mfma_f32_32x32x16_bf16 v[18:33], v[178:181], v[170:173], v[18:33]
	global_load_dwordx4 v[106:109], v[106:107], off
	v_mfma_f32_32x32x16_bf16 v[2:17], v[178:181], v[174:177], v[2:17]
	global_load_dwordx4 v[110:113], v[110:111], off
	ds_read_b128 v[166:169], v0 offset:64
	ds_read_b128 v[170:173], v139 offset:18496
	ds_read_b128 v[174:177], v139 offset:23104
	ds_read_b128 v[178:181], v0 offset:4672
	s_waitcnt lgkmcnt(4)
	v_mfma_f32_32x32x16_bf16 v[50:65], v[182:185], v[186:189], v[50:65]
	global_load_dwordx4 v[114:117], v[114:115], off
	s_waitcnt vmcnt(5)
	ds_write_b128 v138, v[74:77] offset:36864
	v_mfma_f32_32x32x16_bf16 v[34:49], v[182:185], v[190:193], v[34:49]
	global_load_dwordx4 v[118:121], v[118:119], off
	ds_write_b128 v140, v[78:81] offset:36864
	v_mfma_f32_32x32x16_bf16 v[18:33], v[194:197], v[186:189], v[18:33]
	global_load_dwordx4 v[146:149], v[160:161], off
	ds_write_b128 v142, v[82:85] offset:36864
	v_mfma_f32_32x32x16_bf16 v[2:17], v[194:197], v[190:193], v[2:17]
	global_load_dwordx4 v[150:153], v[158:159], off
	ds_write_b128 v144, v[86:89] offset:36864
	ds_read_b128 v[182:185], v0 offset:96
	ds_read_b128 v[186:189], v139 offset:18528
	ds_read_b128 v[190:193], v139 offset:23136
	ds_read_b128 v[194:197], v0 offset:4704
	s_waitcnt lgkmcnt(8)
	v_mfma_f32_32x32x16_bf16 v[50:65], v[166:169], v[170:173], v[50:65]
	ds_write_b128 v138, v[90:93] offset:55296
	v_mfma_f32_32x32x16_bf16 v[34:49], v[166:169], v[174:177], v[34:49]
	ds_write_b128 v140, v[94:97] offset:55296
	v_mfma_f32_32x32x16_bf16 v[18:33], v[178:181], v[170:173], v[18:33]
	ds_write_b128 v142, v[66:69] offset:55296
	v_mfma_f32_32x32x16_bf16 v[2:17], v[178:181], v[174:177], v[2:17]
	ds_write_b128 v144, v[70:73] offset:55296
	s_waitcnt lgkmcnt(4)
	v_mfma_f32_32x32x16_bf16 v[50:65], v[182:185], v[186:189], v[50:65]
	s_min_u32 s1, s0, 12
	s_lshl_b32 s14, s1, 7
	v_mfma_f32_32x32x16_bf16 v[34:49], v[182:185], v[190:193], v[34:49]
	v_lshl_add_u64 v[66:67], v[122:123], 0, s[14:15]
	v_lshl_add_u64 v[68:69], v[124:125], 0, s[14:15]
	v_mfma_f32_32x32x16_bf16 v[18:33], v[194:197], v[186:189], v[18:33]
	v_lshl_add_u64 v[70:71], v[126:127], 0, s[14:15]
	v_lshl_add_u64 v[72:73], v[128:129], 0, s[14:15]
	v_mfma_f32_32x32x16_bf16 v[2:17], v[194:197], v[190:193], v[2:17]
	v_lshl_add_u64 v[90:91], v[130:131], 0, s[14:15]
	v_lshl_add_u64 v[94:95], v[132:133], 0, s[14:15]
	s_setprio 0
	s_waitcnt lgkmcnt(0)
	s_barrier
	ds_read_b128 v[166:169], v0 offset:36864
	ds_read_b128 v[170:173], v139 offset:55296
	ds_read_b128 v[174:177], v139 offset:59904
	ds_read_b128 v[178:181], v0 offset:41472
	v_lshl_add_u64 v[154:155], v[134:135], 0, s[14:15]
	v_lshl_add_u64 v[156:157], v[136:137], 0, s[14:15]
	s_setprio 1
	ds_read_b128 v[182:185], v0 offset:36896
	ds_read_b128 v[186:189], v139 offset:55328
	ds_read_b128 v[190:193], v139 offset:59936
	ds_read_b128 v[194:197], v0 offset:41504
	s_waitcnt lgkmcnt(4)
	v_mfma_f32_32x32x16_bf16 v[50:65], v[166:169], v[170:173], v[50:65]
	global_load_dwordx4 v[74:77], v[66:67], off offset:384
	v_mfma_f32_32x32x16_bf16 v[34:49], v[166:169], v[174:177], v[34:49]
	global_load_dwordx4 v[78:81], v[68:69], off offset:384
	v_mfma_f32_32x32x16_bf16 v[18:33], v[178:181], v[170:173], v[18:33]
	global_load_dwordx4 v[82:85], v[70:71], off offset:384
	v_mfma_f32_32x32x16_bf16 v[2:17], v[178:181], v[174:177], v[2:17]
	global_load_dwordx4 v[86:89], v[72:73], off offset:384
	ds_read_b128 v[166:169], v0 offset:36928
	ds_read_b128 v[170:173], v139 offset:55360
	ds_read_b128 v[174:177], v139 offset:59968
	ds_read_b128 v[178:181], v0 offset:41536
	s_waitcnt lgkmcnt(4)
	v_mfma_f32_32x32x16_bf16 v[50:65], v[182:185], v[186:189], v[50:65]
	global_load_dwordx4 v[90:93], v[90:91], off offset:384
	s_waitcnt vmcnt(5)
	ds_write_b128 v138, v[98:101]
	v_mfma_f32_32x32x16_bf16 v[34:49], v[182:185], v[190:193], v[34:49]
	global_load_dwordx4 v[94:97], v[94:95], off offset:384
	ds_write_b128 v140, v[102:105]
	v_mfma_f32_32x32x16_bf16 v[18:33], v[194:197], v[186:189], v[18:33]
	global_load_dwordx4 v[66:69], v[154:155], off offset:384
	ds_write_b128 v142, v[106:109]
	v_mfma_f32_32x32x16_bf16 v[2:17], v[194:197], v[190:193], v[2:17]
	global_load_dwordx4 v[70:73], v[156:157], off offset:384
	ds_write_b128 v144, v[110:113]
	ds_read_b128 v[182:185], v0 offset:36960
	ds_read_b128 v[186:189], v139 offset:55392
	ds_read_b128 v[190:193], v139 offset:60000
	ds_read_b128 v[194:197], v0 offset:41568
	s_waitcnt lgkmcnt(8)
	v_mfma_f32_32x32x16_bf16 v[50:65], v[166:169], v[170:173], v[50:65]
	ds_write_b128 v138, v[114:117] offset:18432
	v_mfma_f32_32x32x16_bf16 v[34:49], v[166:169], v[174:177], v[34:49]
	ds_write_b128 v140, v[118:121] offset:18432
	v_mfma_f32_32x32x16_bf16 v[18:33], v[178:181], v[170:173], v[18:33]
	ds_write_b128 v142, v[150:153] offset:18432
	v_mfma_f32_32x32x16_bf16 v[2:17], v[178:181], v[174:177], v[2:17]
	ds_write_b128 v144, v[146:149] offset:18432
	s_waitcnt lgkmcnt(4)
	v_mfma_f32_32x32x16_bf16 v[50:65], v[182:185], v[186:189], v[50:65]
	s_cmp_lt_u32 s0, 14
	v_mfma_f32_32x32x16_bf16 v[34:49], v[182:185], v[190:193], v[34:49]
	v_mfma_f32_32x32x16_bf16 v[18:33], v[194:197], v[186:189], v[18:33]
	v_mfma_f32_32x32x16_bf16 v[2:17], v[194:197], v[190:193], v[2:17]
	s_setprio 0
	s_waitcnt lgkmcnt(0)
	s_barrier
	s_branch .LBB0_1956
; #define G_STORE(ST, S, unused) do { char* d_ = smem + (ST) * STAGE; \
;     *(uint4*)(d_ + alo[0]) = S##a0; *(uint4*)(d_ + alo[1]) = S##a1; *(uint4*)(d_ + alo[2]) = S##a2; *(uint4*)(d_ + alo[3]) = S##a3; \
;     *(uint4*)(d_ + blo[0]) = S##b0; *(uint4*)(d_ + blo[1]) = S##b1; \
;     if (NBCH == 4) { *(uint4*)(d_ + blo[NBCH - 2]) = S##b2; *(uint4*)(d_ + blo[NBCH - 1]) = S##b3; } } while (0)
; template <int NJ, class RowA>
; DI void gemm_main(f32x16 (&acc)[2][NJ], const bf16_t* __restrict__ A, RowA rowA, size_t kstrideA, int m0, int Mmax,
;                   const bf16_t* __restrict__ Bt, size_t ldb, int n0, int nk, char* smem) {
;     ...
;   __syncthreads();
;   G_LOAD(x0, 0, 0);
;   G_LOAD(x1, 0, 1);
;   G_STORE(0, x0, 0);
;   __syncthreads();
; #pragma unroll 1
;   for (int kt = 0; kt < nk; kt += 2) {
;     G_LOAD(x0, 0, (kt + 2 < nk ? kt + 2 : nk - 1));
;     G_COMPUTE(0);
;     G_STORE(1, x1, 0);
;     __syncthreads();
;     G_LOAD(x1, 0, (kt + 3 < nk ? kt + 3 : nk - 1));
;     G_COMPUTE(1);
;     G_STORE(0, x0, 0);
;     __syncthreads();
;   }
.Lpeel_tail_1956:
	ds_read_b128 v[166:169], v0
	ds_read_b128 v[170:173], v139 offset:18432
	ds_read_b128 v[174:177], v139 offset:23040
	ds_read_b128 v[178:181], v0 offset:4608
	s_add_i32 s1, s0, 4
	s_min_u32 s1, s1, 15
	s_lshl_b32 s14, s1, 7
	v_lshl_add_u64 v[98:99], v[122:123], 0, s[14:15]
	v_lshl_add_u64 v[102:103], v[124:125], 0, s[14:15]
	v_lshl_add_u64 v[106:107], v[126:127], 0, s[14:15]
	v_lshl_add_u64 v[110:111], v[128:129], 0, s[14:15]
	v_lshl_add_u64 v[114:115], v[130:131], 0, s[14:15]
	v_lshl_add_u64 v[118:119], v[132:133], 0, s[14:15]
	s_add_i32 s0, s0, 2
	v_lshl_add_u64 v[158:159], v[134:135], 0, s[14:15]
	v_lshl_add_u64 v[160:161], v[136:137], 0, s[14:15]
	s_setprio 1
	ds_read_b128 v[182:185], v0 offset:32
	ds_read_b128 v[186:189], v139 offset:18464
	ds_read_b128 v[190:193], v139 offset:23072
	ds_read_b128 v[194:197], v0 offset:4640
	s_waitcnt lgkmcnt(4)
	v_mfma_f32_32x32x16_bf16 v[50:65], v[166:169], v[170:173], v[50:65]
	v_mfma_f32_32x32x16_bf16 v[34:49], v[166:169], v[174:177], v[34:49]
	v_mfma_f32_32x32x16_bf16 v[18:33], v[178:181], v[170:173], v[18:33]
	v_mfma_f32_32x32x16_bf16 v[2:17], v[178:181], v[174:177], v[2:17]
	ds_read_b128 v[166:169], v0 offset:64
	ds_read_b128 v[170:173], v139 offset:18496
	ds_read_b128 v[174:177], v139 offset:23104
	ds_read_b128 v[178:181], v0 offset:4672
	s_waitcnt lgkmcnt(4)
	v_mfma_f32_32x32x16_bf16 v[50:65], v[182:185], v[186:189], v[50:65]
	v_mfma_f32_32x32x16_bf16 v[34:49], v[182:185], v[190:193], v[34:49]
	v_mfma_f32_32x32x16_bf16 v[18:33], v[194:197], v[186:189], v[18:33]
	v_mfma_f32_32x32x16_bf16 v[2:17], v[194:197], v[190:193], v[2:17]
	ds_read_b128 v[182:185], v0 offset:96
	ds_read_b128 v[186:189], v139 offset:18528
	ds_read_b128 v[190:193], v139 offset:23136
	ds_read_b128 v[194:197], v0 offset:4704
	s_waitcnt lgkmcnt(4)
	v_mfma_f32_32x32x16_bf16 v[50:65], v[166:169], v[170:173], v[50:65]
	s_waitcnt vmcnt(0)
	ds_write_b128 v138, v[74:77] offset:36864
	v_mfma_f32_32x32x16_bf16 v[34:49], v[166:169], v[174:177], v[34:49]
	ds_write_b128 v140, v[78:81] offset:36864
	v_mfma_f32_32x32x16_bf16 v[18:33], v[178:181], v[170:173], v[18:33]
	ds_write_b128 v142, v[82:85] offset:36864
	v_mfma_f32_32x32x16_bf16 v[2:17], v[178:181], v[174:177], v[2:17]
	ds_write_b128 v144, v[86:89] offset:36864
	s_waitcnt lgkmcnt(4)
	v_mfma_f32_32x32x16_bf16 v[50:65], v[182:185], v[186:189], v[50:65]
	ds_write_b128 v138, v[90:93] offset:55296
	v_mfma_f32_32x32x16_bf16 v[34:49], v[182:185], v[190:193], v[34:49]
	ds_write_b128 v140, v[94:97] offset:55296
	v_mfma_f32_32x32x16_bf16 v[18:33], v[194:197], v[186:189], v[18:33]
	ds_write_b128 v142, v[66:69] offset:55296
	v_mfma_f32_32x32x16_bf16 v[2:17], v[194:197], v[190:193], v[2:17]
	ds_write_b128 v144, v[70:73] offset:55296
	s_setprio 0
	s_min_u32 s1, s0, 12
	s_lshl_b32 s14, s1, 7
	v_lshl_add_u64 v[66:67], v[122:123], 0, s[14:15]
	v_lshl_add_u64 v[68:69], v[124:125], 0, s[14:15]
	v_lshl_add_u64 v[70:71], v[126:127], 0, s[14:15]
	v_lshl_add_u64 v[72:73], v[128:129], 0, s[14:15]
	v_lshl_add_u64 v[90:91], v[130:131], 0, s[14:15]
	v_lshl_add_u64 v[94:95], v[132:133], 0, s[14:15]
	s_waitcnt lgkmcnt(0)
	s_barrier
	ds_read_b128 v[166:169], v0 offset:36864
	ds_read_b128 v[170:173], v139 offset:55296
	ds_read_b128 v[174:177], v139 offset:59904
	ds_read_b128 v[178:181], v0 offset:41472
	v_lshl_add_u64 v[154:155], v[134:135], 0, s[14:15]
	v_lshl_add_u64 v[156:157], v[136:137], 0, s[14:15]
	s_setprio 1
	ds_read_b128 v[182:185], v0 offset:36896
	ds_read_b128 v[186:189], v139 offset:55328
	ds_read_b128 v[190:193], v139 offset:59936
	ds_read_b128 v[194:197], v0 offset:41504
	s_waitcnt lgkmcnt(4)
	v_mfma_f32_32x32x16_bf16 v[50:65], v[166:169], v[170:173], v[50:65]
	s_cmp_lt_u32 s0, 14
	v_mfma_f32_32x32x16_bf16 v[34:49], v[166:169], v[174:177], v[34:49]
	v_mfma_f32_32x32x16_bf16 v[18:33], v[178:181], v[170:173], v[18:33]
	v_mfma_f32_32x32x16_bf16 v[2:17], v[178:181], v[174:177], v[2:17]
	ds_read_b128 v[166:169], v0 offset:36928
	ds_read_b128 v[170:173], v139 offset:55360
	ds_read_b128 v[174:177], v139 offset:59968
	ds_read_b128 v[178:181], v0 offset:41536
	s_waitcnt lgkmcnt(4)
	v_mfma_f32_32x32x16_bf16 v[50:65], v[182:185], v[186:189], v[50:65]
	v_mfma_f32_32x32x16_bf16 v[34:49], v[182:185], v[190:193], v[34:49]
	v_mfma_f32_32x32x16_bf16 v[18:33], v[194:197], v[186:189], v[18:33]
	v_mfma_f32_32x32x16_bf16 v[2:17], v[194:197], v[190:193], v[2:17]
	ds_read_b128 v[182:185], v0 offset:36960
	ds_read_b128 v[186:189], v139 offset:55392
	ds_read_b128 v[190:193], v139 offset:60000
	ds_read_b128 v[194:197], v0 offset:41568
	s_waitcnt lgkmcnt(4)
	v_mfma_f32_32x32x16_bf16 v[50:65], v[166:169], v[170:173], v[50:65]
	v_mfma_f32_32x32x16_bf16 v[34:49], v[166:169], v[174:177], v[34:49]
	v_mfma_f32_32x32x16_bf16 v[18:33], v[178:181], v[170:173], v[18:33]
	v_mfma_f32_32x32x16_bf16 v[2:17], v[178:181], v[174:177], v[2:17]
	s_waitcnt lgkmcnt(0)
	v_mfma_f32_32x32x16_bf16 v[50:65], v[182:185], v[186:189], v[50:65]
	v_mfma_f32_32x32x16_bf16 v[34:49], v[182:185], v[190:193], v[34:49]
	v_mfma_f32_32x32x16_bf16 v[18:33], v[194:197], v[186:189], v[18:33]
	v_mfma_f32_32x32x16_bf16 v[2:17], v[194:197], v[190:193], v[2:17]
	s_setprio 0
	s_waitcnt lgkmcnt(0)
	s_barrier
; #define TIDX (tid_launder())
; DI unsigned pack2(float a, float b) { hwf2 v = {a, b}; hwbf2 r = __builtin_convertvector(v, hwbf2); return __builtin_bit_cast(unsigned, r); }
; DI int crow(int reg, int hh) { return (reg & 3) + 8 * (reg >> 2) + 4 * hh; }
; DI float siluf(float x) { return x * __builtin_amdgcn_rcpf(1.f + __expf(-x)); }
; template <int NJ>
; DI void acc_to_ct(const f32x16 (&acc)[2][NJ], float* Ct) {
;   const int lane = TIDX & 63, wid = TIDX >> 6, wm = wid >> 1, wn = wid & 1;
;   const int r = lane & 31, hh = lane >> 5;
; #pragma unroll
;   for (int i = 0; i < 2; ++i)
; #pragma unroll
;     for (int j = 0; j < NJ; ++j)
; #pragma unroll
;       for (int e = 0; e < 16; ++e) Ct[(wm * 64 + i * 32 + crow(e, hh)) * 132 + wn * 32 * NJ + j * 32 + r] = acc[i][j][e];
;   __syncthreads();
; DI void epi_store64(const float* Ct, int cb, const float* rn, int grp, const float* gain, bool silu, const float* bias,
;                     bf16_t* dst, size_t ldd, int dcol0, int m0, int Mmax) {
;   const int tid = TIDX, c = (tid & 15) * 4;
;   float4 gv = make_float4(1.f, 1.f, 1.f, 1.f), bv = make_float4(0.f, 0.f, 0.f, 0.f);
;   if (rn) gv = *(const float4*)(gain + c);
;   if (bias) bv = *(const float4*)(bias + c);
; #pragma unroll
;   for (int q = 0; q < 8; ++q) {
;     const int row = (tid >> 4) + 16 * q;
;     float4 v = *(const float4*)(Ct + row * 132 + cb + c);
;     v.x += bv.x; v.y += bv.y; v.z += bv.z; v.w += bv.w;
;     if (rn) { const float sc = rn[row * 2 + grp]; v.x *= sc * gv.x; v.y *= sc * gv.y; v.z *= sc * gv.z; v.w *= sc * gv.w; }
;     if (silu) { v.x = siluf(v.x); v.y = siluf(v.y); v.z = siluf(v.z); v.w = siluf(v.w); }
;     uint2 o; o.x = pack2(v.x, v.y); o.y = pack2(v.z, v.w);
;     *(uint2*)(dst + (size_t)(m0 + row) * ldd + dcol0 + c) = o;
;   }
; }
	v_mov_b32_e32 v0, v230
	s_waitcnt vmcnt(1)
	v_mov_b32_e32 v66, v230
	v_and_b32_e32 v67, 31, v0
	v_lshrrev_b32_e32 v0, 3, v0
	v_and_b32_e32 v0, 4, v0
	v_lshrrev_b32_e32 v68, 1, v66
	v_and_or_b32 v0, v68, s47, v0
	v_and_or_b32 v66, v66, 64, v67
	v_mul_lo_u32 v0, v0, s79
	v_lshl_add_u32 v0, v66, 2, v0
	ds_write2_b32 v0, v50, v34 offset1:32
	ds_write2_b32 v0, v51, v35 offset0:132 offset1:164
	v_add_u32_e32 v34, 0x400, v0
	ds_write2_b32 v34, v52, v36 offset0:8 offset1:40
	ds_write2_b32 v34, v53, v37 offset0:140 offset1:172
	v_add_u32_e32 v34, 0x1000, v0
	ds_write2_b32 v34, v54, v38 offset0:32 offset1:64
	ds_write2_b32 v34, v55, v39 offset0:164 offset1:196
	v_add_u32_e32 v34, 0x1400, v0
	ds_write2_b32 v34, v56, v40 offset0:40 offset1:72
	ds_write2_b32 v34, v57, v41 offset0:172 offset1:204
	v_add_u32_e32 v34, 0x2000, v0
	ds_write2_b32 v34, v58, v42 offset0:64 offset1:96
	ds_write2_b32 v34, v59, v43 offset0:196 offset1:228
	v_add_u32_e32 v34, 0x2400, v0
	ds_write2_b32 v34, v60, v44 offset0:72 offset1:104
	ds_write2_b32 v34, v61, v45 offset0:204 offset1:236
	v_add_u32_e32 v34, 0x3000, v0
	ds_write2_b32 v34, v62, v46 offset0:96 offset1:128
	v_add_u32_e32 v34, 0x3200, v0
	ds_write2_b32 v34, v63, v47 offset0:100 offset1:132
	v_add_u32_e32 v34, 0x3400, v0
	ds_write2_b32 v34, v64, v48 offset0:104 offset1:136
	v_add_u32_e32 v34, 0x3600, v0
	ds_write2_b32 v34, v65, v49 offset0:108 offset1:140
	v_add_u32_e32 v34, 0x4000, v0
	ds_write2_b32 v34, v18, v2 offset0:128 offset1:160
	v_add_u32_e32 v2, 0x4400, v0
	ds_write2_b32 v2, v19, v3 offset0:4 offset1:36
	ds_write2_b32 v2, v20, v4 offset0:136 offset1:168
	v_add_u32_e32 v2, 0x4800, v0
	ds_write2_b32 v2, v21, v5 offset0:12 offset1:44
	v_add_u32_e32 v2, 0x5000, v0
	ds_write2_b32 v2, v22, v6 offset0:160 offset1:192
	v_add_u32_e32 v2, 0x5400, v0
	ds_write2_b32 v2, v23, v7 offset0:36 offset1:68
	ds_write2_b32 v2, v24, v8 offset0:168 offset1:200
	v_add_u32_e32 v2, 0x5800, v0
	ds_write2_b32 v2, v25, v9 offset0:44 offset1:76
	v_add_u32_e32 v2, 0x6000, v0
	ds_write2_b32 v2, v26, v10 offset0:192 offset1:224
	v_add_u32_e32 v2, 0x6400, v0
	ds_write2_b32 v2, v27, v11 offset0:68 offset1:100
	ds_write2_b32 v2, v28, v12 offset0:200 offset1:232
	v_add_u32_e32 v2, 0x6800, v0
	ds_write2_b32 v2, v29, v13 offset0:76 offset1:108
	v_add_u32_e32 v2, 0x7200, v0
	ds_write2_b32 v2, v30, v14 offset0:96 offset1:128
	v_add_u32_e32 v2, 0x7400, v0
	ds_write2_b32 v2, v31, v15 offset0:100 offset1:132
	v_add_u32_e32 v2, 0x7600, v0
	v_add_u32_e32 v0, 0x7800, v0
	s_cmp_gt_i32 s12, 3
	s_mov_b64 s[0:1], -1
	ds_write2_b32 v2, v32, v16 offset0:104 offset1:136
	ds_write2_b32 v0, v33, v17 offset0:108 offset1:140
	s_waitcnt lgkmcnt(0)
	s_barrier
	s_cbranch_scc0 .LBB0_2086
	s_cmp_lg_u32 s12, 4
	s_cbranch_scc0 .LBB0_2045
	s_cmp_gt_u32 s12, 8
	s_cbranch_scc0 .LBB0_2042
	s_ashr_i32 s0, s3, 7
	s_add_i32 s4, s0, s4
	s_ashr_i32 s0, s11, 31
	s_lshr_b32 s0, s0, 21
	s_add_i32 s0, s11, s0
	s_and_b32 s0, s0, 0xfffff800
	s_sub_i32 s13, s11, s0
	s_cmp_lt_i32 s12, 11
	s_mov_b64 s[0:1], -1
	s_cbranch_scc1 .LBB0_2012
	s_cmp_lt_i32 s12, 12
	s_cbranch_scc1 .LBB0_1982
	s_cmp_lg_u32 s12, 12
	s_cbranch_scc0 .LBB0_1968
	s_cmp_gt_u32 s12, 24
	s_mov_b32 s3, s15
	s_cbranch_scc0 .LBB0_1965
	v_mov_b32_e32 v0, v230
	v_readlane_b32 s16, v252, 57
	s_lshl_b64 s[0:1], s[2:3], 1
	v_lshlrev_b32_e32 v2, 2, v0
	v_readlane_b32 s28, v253, 5
	v_and_b32_e32 v4, 60, v2
	v_readlane_b32 s29, v253, 6
	s_add_u32 s0, s28, s0
	v_ashrrev_i32_e32 v10, 4, v0
	s_addc_u32 s1, s29, s1
	v_lshlrev_b32_e32 v0, 1, v4
	v_lshl_add_u64 v[2:3], s[0:1], 0, v[0:1]
	v_mul_lo_u32 v0, v10, s79
	v_lshl_add_u32 v0, v4, 2, v0
	ds_read_b128 v[4:7], v0
	s_movk_i32 s6, 0xe700
	s_mov_b32 s7, -1
	v_lshl_add_u64 v[2:3], v[2:3], 0, s[6:7]
	v_readlane_b32 s17, v252, 58
	s_waitcnt lgkmcnt(0)
	v_pk_add_f32 v[4:5], v[4:5], 0 op_sel_hi:[1,0]
	v_pk_add_f32 v[6:7], v[6:7], 0 op_sel_hi:[1,0]
	v_mul_f32_e32 v8, 0xbfb8aa3b, v4
	v_mul_f32_e32 v9, 0xbfb8aa3b, v5
	v_exp_f32_e32 v8, v8
	v_exp_f32_e32 v9, v9
	v_readlane_b32 s18, v252, 59
	v_readlane_b32 s19, v252, 60
	v_add_f32_e32 v8, 1.0, v8
	v_add_f32_e32 v9, 1.0, v9
	v_rcp_f32_e32 v8, v8
	v_rcp_f32_e32 v9, v9
	v_readlane_b32 s20, v252, 61
	v_readlane_b32 s21, v252, 62
	v_readlane_b32 s22, v252, 63
	v_pk_mul_f32 v[4:5], v[4:5], v[8:9]
	v_mul_f32_e32 v8, 0xbfb8aa3b, v6
	v_mul_f32_e32 v9, 0xbfb8aa3b, v7
	v_exp_f32_e32 v8, v8
	v_exp_f32_e32 v9, v9
	v_readlane_b32 s23, v253, 0
	v_readlane_b32 s24, v253, 1
	v_add_f32_e32 v8, 1.0, v8
	v_add_f32_e32 v9, 1.0, v9
	v_rcp_f32_e32 v8, v8
	v_rcp_f32_e32 v9, v9
	v_readlane_b32 s25, v253, 2
	v_readlane_b32 s26, v253, 3
	v_readlane_b32 s27, v253, 4
	v_pk_mul_f32 v[6:7], v[6:7], v[8:9]
	v_cvt_pk_bf16_f32 v8, v4, v5
	v_add_u32_e32 v4, s11, v10
	v_ashrrev_i32_e32 v5, 31, v4
	v_cvt_pk_bf16_f32 v9, v6, v7
	v_lshlrev_b64 v[6:7], 11, v[4:5]
	v_lshl_add_u64 v[6:7], v[2:3], 0, v[6:7]
	global_store_dwordx2 v[6:7], v[8:9], off
	ds_read_b128 v[6:9], v0 offset:8448
	v_readlane_b32 s30, v253, 7
	v_readlane_b32 s31, v253, 8
	s_waitcnt lgkmcnt(0)
	v_pk_add_f32 v[6:7], v[6:7], 0 op_sel_hi:[1,0]
	s_nop 0
	v_mul_f32_e32 v5, 0xbfb8aa3b, v6
	v_exp_f32_e32 v5, v5
	v_pk_add_f32 v[8:9], v[8:9], 0 op_sel_hi:[1,0]
	v_add_f32_e32 v5, 1.0, v5
	v_rcp_f32_e32 v10, v5
	v_mul_f32_e32 v5, 0xbfb8aa3b, v7
	v_exp_f32_e32 v5, v5
	s_nop 0
	v_add_f32_e32 v5, 1.0, v5
	v_rcp_f32_e32 v11, v5
	v_mul_f32_e32 v5, 0xbfb8aa3b, v8
	v_exp_f32_e32 v5, v5
	v_pk_mul_f32 v[6:7], v[6:7], v[10:11]
	s_nop 0
	v_cvt_pk_bf16_f32 v6, v6, v7
	v_add_f32_e32 v5, 1.0, v5
	v_rcp_f32_e32 v10, v5
	v_mul_f32_e32 v5, 0xbfb8aa3b, v9
	v_exp_f32_e32 v5, v5
	s_nop 0
	v_add_f32_e32 v5, 1.0, v5
	v_rcp_f32_e32 v11, v5
	s_nop 0
	v_pk_mul_f32 v[8:9], v[8:9], v[10:11]
	s_nop 0
	v_cvt_pk_bf16_f32 v7, v8, v9
	v_add_u32_e32 v8, 16, v4
	v_ashrrev_i32_e32 v9, 31, v8
	v_lshlrev_b64 v[8:9], 11, v[8:9]
	v_lshl_add_u64 v[8:9], v[2:3], 0, v[8:9]
	global_store_dwordx2 v[8:9], v[6:7], off
	ds_read_b128 v[6:9], v0 offset:16896
	s_waitcnt lgkmcnt(0)
; #define TIDX (tid_launder())
; DI unsigned pack2(float a, float b) { hwf2 v = {a, b}; hwbf2 r = __builtin_convertvector(v, hwbf2); return __builtin_bit_cast(unsigned, r); }
; DI float siluf(float x) { return x * __builtin_amdgcn_rcpf(1.f + __expf(-x)); }
; DI void epi_store64(const float* Ct, int cb, const float* rn, int grp, const float* gain, bool silu, const float* bias,
;                     bf16_t* dst, size_t ldd, int dcol0, int m0, int Mmax) {
;   const int tid = TIDX, c = (tid & 15) * 4;
;   float4 gv = make_float4(1.f, 1.f, 1.f, 1.f), bv = make_float4(0.f, 0.f, 0.f, 0.f);
;   if (rn) gv = *(const float4*)(gain + c);
;   if (bias) bv = *(const float4*)(bias + c);
; #pragma unroll
;   for (int q = 0; q < 8; ++q) {
;     const int row = (tid >> 4) + 16 * q;
;     float4 v = *(const float4*)(Ct + row * 132 + cb + c);
;     v.x += bv.x; v.y += bv.y; v.z += bv.z; v.w += bv.w;
;     if (rn) { const float sc = rn[row * 2 + grp]; v.x *= sc * gv.x; v.y *= sc * gv.y; v.z *= sc * gv.z; v.w *= sc * gv.w; }
;     if (silu) { v.x = siluf(v.x); v.y = siluf(v.y); v.z = siluf(v.z); v.w = siluf(v.w); }
;     uint2 o; o.x = pack2(v.x, v.y); o.y = pack2(v.z, v.w);
;     *(uint2*)(dst + (size_t)(m0 + row) * ldd + dcol0 + c) = o;
;   }
; }
	v_pk_add_f32 v[6:7], v[6:7], 0 op_sel_hi:[1,0]
	s_nop 0
	v_mul_f32_e32 v5, 0xbfb8aa3b, v6
	v_exp_f32_e32 v5, v5
	v_pk_add_f32 v[8:9], v[8:9], 0 op_sel_hi:[1,0]
	v_add_f32_e32 v5, 1.0, v5
	v_rcp_f32_e32 v10, v5
	v_mul_f32_e32 v5, 0xbfb8aa3b, v7
	v_exp_f32_e32 v5, v5
	s_nop 0
	v_add_f32_e32 v5, 1.0, v5
	v_rcp_f32_e32 v11, v5
	v_mul_f32_e32 v5, 0xbfb8aa3b, v8
	v_exp_f32_e32 v5, v5
	v_pk_mul_f32 v[6:7], v[6:7], v[10:11]
	s_nop 0
	v_cvt_pk_bf16_f32 v6, v6, v7
	v_add_f32_e32 v5, 1.0, v5
	v_rcp_f32_e32 v10, v5
	v_mul_f32_e32 v5, 0xbfb8aa3b, v9
	v_exp_f32_e32 v5, v5
	s_nop 0
	v_add_f32_e32 v5, 1.0, v5
	v_rcp_f32_e32 v11, v5
	s_nop 0
	v_pk_mul_f32 v[8:9], v[8:9], v[10:11]
	s_nop 0
	v_cvt_pk_bf16_f32 v7, v8, v9
	v_add_u32_e32 v8, 32, v4
	v_ashrrev_i32_e32 v9, 31, v8
	v_lshlrev_b64 v[8:9], 11, v[8:9]
	v_lshl_add_u64 v[8:9], v[2:3], 0, v[8:9]
	global_store_dwordx2 v[8:9], v[6:7], off
	ds_read_b128 v[6:9], v0 offset:25344
	s_waitcnt lgkmcnt(0)
	v_pk_add_f32 v[6:7], v[6:7], 0 op_sel_hi:[1,0]
	s_nop 0
	v_mul_f32_e32 v5, 0xbfb8aa3b, v6
	v_exp_f32_e32 v5, v5
	v_pk_add_f32 v[8:9], v[8:9], 0 op_sel_hi:[1,0]
	v_add_f32_e32 v5, 1.0, v5
	v_rcp_f32_e32 v10, v5
	v_mul_f32_e32 v5, 0xbfb8aa3b, v7
	v_exp_f32_e32 v5, v5
	s_nop 0
	v_add_f32_e32 v5, 1.0, v5
	v_rcp_f32_e32 v11, v5
	v_mul_f32_e32 v5, 0xbfb8aa3b, v8
	v_exp_f32_e32 v5, v5
	v_pk_mul_f32 v[6:7], v[6:7], v[10:11]
	s_nop 0
	v_cvt_pk_bf16_f32 v6, v6, v7
	v_add_f32_e32 v5, 1.0, v5
	v_rcp_f32_e32 v10, v5
	v_mul_f32_e32 v5, 0xbfb8aa3b, v9
	v_exp_f32_e32 v5, v5
	s_nop 0
	v_add_f32_e32 v5, 1.0, v5
	v_rcp_f32_e32 v11, v5
	s_nop 0
	v_pk_mul_f32 v[8:9], v[8:9], v[10:11]
	s_nop 0
	v_cvt_pk_bf16_f32 v7, v8, v9
	v_add_u32_e32 v8, 48, v4
	v_ashrrev_i32_e32 v9, 31, v8
	v_lshlrev_b64 v[8:9], 11, v[8:9]
	v_lshl_add_u64 v[8:9], v[2:3], 0, v[8:9]
	global_store_dwordx2 v[8:9], v[6:7], off
	ds_read_b128 v[6:9], v0 offset:33792
	s_waitcnt lgkmcnt(0)
	v_pk_add_f32 v[6:7], v[6:7], 0 op_sel_hi:[1,0]
	s_nop 0
	v_mul_f32_e32 v5, 0xbfb8aa3b, v6
	v_exp_f32_e32 v5, v5
	v_pk_add_f32 v[8:9], v[8:9], 0 op_sel_hi:[1,0]
	v_add_f32_e32 v5, 1.0, v5
	v_rcp_f32_e32 v10, v5
	v_mul_f32_e32 v5, 0xbfb8aa3b, v7
	v_exp_f32_e32 v5, v5
	s_nop 0
	v_add_f32_e32 v5, 1.0, v5
	v_rcp_f32_e32 v11, v5
	v_mul_f32_e32 v5, 0xbfb8aa3b, v8
	v_exp_f32_e32 v5, v5
	v_pk_mul_f32 v[6:7], v[6:7], v[10:11]
	s_nop 0
	v_cvt_pk_bf16_f32 v6, v6, v7
	v_add_f32_e32 v5, 1.0, v5
	v_rcp_f32_e32 v10, v5
	v_mul_f32_e32 v5, 0xbfb8aa3b, v9
	v_exp_f32_e32 v5, v5
	s_nop 0
	v_add_f32_e32 v5, 1.0, v5
	v_rcp_f32_e32 v11, v5
	s_nop 0
	v_pk_mul_f32 v[8:9], v[8:9], v[10:11]
	s_nop 0
	v_cvt_pk_bf16_f32 v7, v8, v9
	v_add_u32_e32 v8, 64, v4
	v_ashrrev_i32_e32 v9, 31, v8
	v_lshlrev_b64 v[8:9], 11, v[8:9]
	v_lshl_add_u64 v[8:9], v[2:3], 0, v[8:9]
	global_store_dwordx2 v[8:9], v[6:7], off
	ds_read_b128 v[6:9], v0 offset:42240
	s_waitcnt lgkmcnt(0)
	v_pk_add_f32 v[6:7], v[6:7], 0 op_sel_hi:[1,0]
	s_nop 0
	v_mul_f32_e32 v5, 0xbfb8aa3b, v6
	v_exp_f32_e32 v5, v5
	v_pk_add_f32 v[8:9], v[8:9], 0 op_sel_hi:[1,0]
	v_add_f32_e32 v5, 1.0, v5
	v_rcp_f32_e32 v10, v5
	v_mul_f32_e32 v5, 0xbfb8aa3b, v7
	v_exp_f32_e32 v5, v5
	s_nop 0
	v_add_f32_e32 v5, 1.0, v5
	v_rcp_f32_e32 v11, v5
	v_mul_f32_e32 v5, 0xbfb8aa3b, v8
	v_exp_f32_e32 v5, v5
	v_pk_mul_f32 v[6:7], v[6:7], v[10:11]
	s_nop 0
	v_cvt_pk_bf16_f32 v6, v6, v7
	v_add_f32_e32 v5, 1.0, v5
	v_rcp_f32_e32 v10, v5
	v_mul_f32_e32 v5, 0xbfb8aa3b, v9
	v_exp_f32_e32 v5, v5
	s_nop 0
	v_add_f32_e32 v5, 1.0, v5
	v_rcp_f32_e32 v11, v5
	s_nop 0
	v_pk_mul_f32 v[8:9], v[8:9], v[10:11]
	s_nop 0
	v_cvt_pk_bf16_f32 v7, v8, v9
	v_add_u32_e32 v8, 0x50, v4
	v_ashrrev_i32_e32 v9, 31, v8
	v_lshlrev_b64 v[8:9], 11, v[8:9]
	v_lshl_add_u64 v[8:9], v[2:3], 0, v[8:9]
	global_store_dwordx2 v[8:9], v[6:7], off
	ds_read_b128 v[6:9], v0 offset:50688
	s_waitcnt lgkmcnt(0)
	v_pk_add_f32 v[6:7], v[6:7], 0 op_sel_hi:[1,0]
	s_nop 0
	v_mul_f32_e32 v5, 0xbfb8aa3b, v6
	v_exp_f32_e32 v5, v5
	v_pk_add_f32 v[8:9], v[8:9], 0 op_sel_hi:[1,0]
	v_add_f32_e32 v5, 1.0, v5
	v_rcp_f32_e32 v10, v5
	v_mul_f32_e32 v5, 0xbfb8aa3b, v7
	v_exp_f32_e32 v5, v5
	s_nop 0
	v_add_f32_e32 v5, 1.0, v5
	v_rcp_f32_e32 v11, v5
	v_mul_f32_e32 v5, 0xbfb8aa3b, v8
	v_exp_f32_e32 v5, v5
	v_pk_mul_f32 v[6:7], v[6:7], v[10:11]
	s_nop 0
	v_cvt_pk_bf16_f32 v6, v6, v7
	v_add_f32_e32 v5, 1.0, v5
	v_rcp_f32_e32 v10, v5
	v_mul_f32_e32 v5, 0xbfb8aa3b, v9
	v_exp_f32_e32 v5, v5
	s_nop 0
	v_add_f32_e32 v5, 1.0, v5
	v_rcp_f32_e32 v11, v5
	s_nop 0
	v_pk_mul_f32 v[8:9], v[8:9], v[10:11]
	s_nop 0
	v_cvt_pk_bf16_f32 v7, v8, v9
	v_add_u32_e32 v8, 0x60, v4
	v_ashrrev_i32_e32 v9, 31, v8
	v_lshlrev_b64 v[8:9], 11, v[8:9]
	v_lshl_add_u64 v[8:9], v[2:3], 0, v[8:9]
	global_store_dwordx2 v[8:9], v[6:7], off
	ds_read_b128 v[6:9], v0 offset:59136
	v_add_u32_e32 v4, 0x70, v4
	v_ashrrev_i32_e32 v5, 31, v4
	v_lshlrev_b64 v[4:5], 11, v[4:5]
	v_lshl_add_u64 v[2:3], v[2:3], 0, v[4:5]
	s_waitcnt lgkmcnt(0)
	v_pk_add_f32 v[6:7], v[6:7], 0 op_sel_hi:[1,0]
	v_pk_add_f32 v[8:9], v[8:9], 0 op_sel_hi:[1,0]
	v_mul_f32_e32 v0, 0xbfb8aa3b, v6
	v_exp_f32_e32 v0, v0
	s_nop 0
	v_add_f32_e32 v0, 1.0, v0
	v_rcp_f32_e32 v10, v0
	v_mul_f32_e32 v0, 0xbfb8aa3b, v7
	v_exp_f32_e32 v0, v0
	s_nop 0
	v_add_f32_e32 v0, 1.0, v0
	v_rcp_f32_e32 v11, v0
	v_mul_f32_e32 v0, 0xbfb8aa3b, v8
	v_exp_f32_e32 v0, v0
	v_pk_mul_f32 v[6:7], v[6:7], v[10:11]
	s_nop 0
	v_cvt_pk_bf16_f32 v6, v6, v7
	v_add_f32_e32 v0, 1.0, v0
	v_rcp_f32_e32 v10, v0
	v_mul_f32_e32 v0, 0xbfb8aa3b, v9
	v_exp_f32_e32 v0, v0
	s_nop 0
	v_add_f32_e32 v0, 1.0, v0
	v_rcp_f32_e32 v11, v0
	v_mov_b32_e32 v0, v230
	v_pk_mul_f32 v[8:9], v[8:9], v[10:11]
	s_nop 0
	v_cvt_pk_bf16_f32 v7, v8, v9
	global_store_dwordx2 v[2:3], v[6:7], off
	s_nop 0
	v_lshlrev_b32_e32 v2, 2, v0
	v_and_b32_e32 v4, 60, v2
	v_ashrrev_i32_e32 v10, 4, v0
	v_lshlrev_b32_e32 v0, 1, v4
	v_lshl_add_u64 v[2:3], s[0:1], 0, v[0:1]
	v_mul_lo_u32 v0, v10, s79
	v_lshl_add_u32 v0, v4, 2, v0
	ds_read_b128 v[4:7], v0 offset:256
	s_movk_i32 s0, 0xe780
	s_mov_b32 s1, -1
	v_lshl_add_u64 v[2:3], v[2:3], 0, s[0:1]
	s_mov_b64 s[0:1], 0
	s_waitcnt lgkmcnt(0)
; #define TIDX (tid_launder())
; DI unsigned pack2(float a, float b) { hwf2 v = {a, b}; hwbf2 r = __builtin_convertvector(v, hwbf2); return __builtin_bit_cast(unsigned, r); }
; DI float siluf(float x) { return x * __builtin_amdgcn_rcpf(1.f + __expf(-x)); }
; DI void epi_store64(const float* Ct, int cb, const float* rn, int grp, const float* gain, bool silu, const float* bias,
;                     bf16_t* dst, size_t ldd, int dcol0, int m0, int Mmax) {
;   const int tid = TIDX, c = (tid & 15) * 4;
;   float4 gv = make_float4(1.f, 1.f, 1.f, 1.f), bv = make_float4(0.f, 0.f, 0.f, 0.f);
;   if (rn) gv = *(const float4*)(gain + c);
;   if (bias) bv = *(const float4*)(bias + c);
; #pragma unroll
;   for (int q = 0; q < 8; ++q) {
;     const int row = (tid >> 4) + 16 * q;
;     float4 v = *(const float4*)(Ct + row * 132 + cb + c);
;     v.x += bv.x; v.y += bv.y; v.z += bv.z; v.w += bv.w;
;     if (rn) { const float sc = rn[row * 2 + grp]; v.x *= sc * gv.x; v.y *= sc * gv.y; v.z *= sc * gv.z; v.w *= sc * gv.w; }
;     if (silu) { v.x = siluf(v.x); v.y = siluf(v.y); v.z = siluf(v.z); v.w = siluf(v.w); }
;     uint2 o; o.x = pack2(v.x, v.y); o.y = pack2(v.z, v.w);
;     *(uint2*)(dst + (size_t)(m0 + row) * ldd + dcol0 + c) = o;
;   }
; }
	v_pk_add_f32 v[4:5], v[4:5], 0 op_sel_hi:[1,0]
	v_pk_add_f32 v[6:7], v[6:7], 0 op_sel_hi:[1,0]
	v_mul_f32_e32 v8, 0xbfb8aa3b, v4
	v_mul_f32_e32 v9, 0xbfb8aa3b, v5
	v_exp_f32_e32 v8, v8
	v_exp_f32_e32 v9, v9
	v_add_f32_e32 v8, 1.0, v8
	v_add_f32_e32 v9, 1.0, v9
	v_rcp_f32_e32 v8, v8
	v_rcp_f32_e32 v9, v9
	s_nop 0
	v_pk_mul_f32 v[4:5], v[4:5], v[8:9]
	v_mul_f32_e32 v8, 0xbfb8aa3b, v6
	v_mul_f32_e32 v9, 0xbfb8aa3b, v7
	v_exp_f32_e32 v8, v8
	v_exp_f32_e32 v9, v9
	v_add_f32_e32 v8, 1.0, v8
	v_add_f32_e32 v9, 1.0, v9
	v_rcp_f32_e32 v8, v8
	v_rcp_f32_e32 v9, v9
	s_nop 0
	v_pk_mul_f32 v[6:7], v[6:7], v[8:9]
	v_cvt_pk_bf16_f32 v8, v4, v5
	v_add_u32_e32 v4, s11, v10
	v_ashrrev_i32_e32 v5, 31, v4
	v_cvt_pk_bf16_f32 v9, v6, v7
	v_lshlrev_b64 v[6:7], 11, v[4:5]
	v_lshl_add_u64 v[6:7], v[2:3], 0, v[6:7]
	global_store_dwordx2 v[6:7], v[8:9], off
	ds_read_b128 v[6:9], v0 offset:8704
	s_waitcnt lgkmcnt(0)
	v_pk_add_f32 v[6:7], v[6:7], 0 op_sel_hi:[1,0]
	s_nop 0
	v_mul_f32_e32 v5, 0xbfb8aa3b, v6
	v_exp_f32_e32 v5, v5
	v_pk_add_f32 v[8:9], v[8:9], 0 op_sel_hi:[1,0]
	v_add_f32_e32 v5, 1.0, v5
	v_rcp_f32_e32 v10, v5
	v_mul_f32_e32 v5, 0xbfb8aa3b, v7
	v_exp_f32_e32 v5, v5
	s_nop 0
	v_add_f32_e32 v5, 1.0, v5
	v_rcp_f32_e32 v11, v5
	v_mul_f32_e32 v5, 0xbfb8aa3b, v8
	v_exp_f32_e32 v5, v5
	v_pk_mul_f32 v[6:7], v[6:7], v[10:11]
	s_nop 0
	v_cvt_pk_bf16_f32 v6, v6, v7
	v_add_f32_e32 v5, 1.0, v5
	v_rcp_f32_e32 v10, v5
	v_mul_f32_e32 v5, 0xbfb8aa3b, v9
	v_exp_f32_e32 v5, v5
	s_nop 0
	v_add_f32_e32 v5, 1.0, v5
	v_rcp_f32_e32 v11, v5
	s_nop 0
	v_pk_mul_f32 v[8:9], v[8:9], v[10:11]
	s_nop 0
	v_cvt_pk_bf16_f32 v7, v8, v9
	v_add_u32_e32 v8, 16, v4
	v_ashrrev_i32_e32 v9, 31, v8
	v_lshlrev_b64 v[8:9], 11, v[8:9]
	v_lshl_add_u64 v[8:9], v[2:3], 0, v[8:9]
	global_store_dwordx2 v[8:9], v[6:7], off
	ds_read_b128 v[6:9], v0 offset:17152
	s_waitcnt lgkmcnt(0)
	v_pk_add_f32 v[6:7], v[6:7], 0 op_sel_hi:[1,0]
	s_nop 0
	v_mul_f32_e32 v5, 0xbfb8aa3b, v6
	v_exp_f32_e32 v5, v5
	v_pk_add_f32 v[8:9], v[8:9], 0 op_sel_hi:[1,0]
	v_add_f32_e32 v5, 1.0, v5
	v_rcp_f32_e32 v10, v5
	v_mul_f32_e32 v5, 0xbfb8aa3b, v7
	v_exp_f32_e32 v5, v5
	s_nop 0
	v_add_f32_e32 v5, 1.0, v5
	v_rcp_f32_e32 v11, v5
	v_mul_f32_e32 v5, 0xbfb8aa3b, v8
	v_exp_f32_e32 v5, v5
	v_pk_mul_f32 v[6:7], v[6:7], v[10:11]
	s_nop 0
	v_cvt_pk_bf16_f32 v6, v6, v7
	v_add_f32_e32 v5, 1.0, v5
	v_rcp_f32_e32 v10, v5
	v_mul_f32_e32 v5, 0xbfb8aa3b, v9
	v_exp_f32_e32 v5, v5
	s_nop 0
	v_add_f32_e32 v5, 1.0, v5
	v_rcp_f32_e32 v11, v5
	s_nop 0
	v_pk_mul_f32 v[8:9], v[8:9], v[10:11]
	s_nop 0
	v_cvt_pk_bf16_f32 v7, v8, v9
	v_add_u32_e32 v8, 32, v4
	v_ashrrev_i32_e32 v9, 31, v8
	v_lshlrev_b64 v[8:9], 11, v[8:9]
	v_lshl_add_u64 v[8:9], v[2:3], 0, v[8:9]
	global_store_dwordx2 v[8:9], v[6:7], off
	ds_read_b128 v[6:9], v0 offset:25600
	s_waitcnt lgkmcnt(0)
	v_pk_add_f32 v[6:7], v[6:7], 0 op_sel_hi:[1,0]
	s_nop 0
	v_mul_f32_e32 v5, 0xbfb8aa3b, v6
	v_exp_f32_e32 v5, v5
	v_pk_add_f32 v[8:9], v[8:9], 0 op_sel_hi:[1,0]
	v_add_f32_e32 v5, 1.0, v5
	v_rcp_f32_e32 v10, v5
	v_mul_f32_e32 v5, 0xbfb8aa3b, v7
	v_exp_f32_e32 v5, v5
	s_nop 0
	v_add_f32_e32 v5, 1.0, v5
	v_rcp_f32_e32 v11, v5
	v_mul_f32_e32 v5, 0xbfb8aa3b, v8
	v_exp_f32_e32 v5, v5
	v_pk_mul_f32 v[6:7], v[6:7], v[10:11]
	s_nop 0
	v_cvt_pk_bf16_f32 v6, v6, v7
	v_add_f32_e32 v5, 1.0, v5
	v_rcp_f32_e32 v10, v5
	v_mul_f32_e32 v5, 0xbfb8aa3b, v9
	v_exp_f32_e32 v5, v5
	s_nop 0
	v_add_f32_e32 v5, 1.0, v5
	v_rcp_f32_e32 v11, v5
	s_nop 0
	v_pk_mul_f32 v[8:9], v[8:9], v[10:11]
	s_nop 0
	v_cvt_pk_bf16_f32 v7, v8, v9
	v_add_u32_e32 v8, 48, v4
	v_ashrrev_i32_e32 v9, 31, v8
	v_lshlrev_b64 v[8:9], 11, v[8:9]
	v_lshl_add_u64 v[8:9], v[2:3], 0, v[8:9]
	global_store_dwordx2 v[8:9], v[6:7], off
	ds_read_b128 v[6:9], v0 offset:34048
	s_waitcnt lgkmcnt(0)
; #define TIDX (tid_launder())
; DI unsigned pack2(float a, float b) { hwf2 v = {a, b}; hwbf2 r = __builtin_convertvector(v, hwbf2); return __builtin_bit_cast(unsigned, r); }
; DI float siluf(float x) { return x * __builtin_amdgcn_rcpf(1.f + __expf(-x)); }
; DI void epi_store64(const float* Ct, int cb, const float* rn, int grp, const float* gain, bool silu, const float* bias,
;                     bf16_t* dst, size_t ldd, int dcol0, int m0, int Mmax) {
;   const int tid = TIDX, c = (tid & 15) * 4;
;   float4 gv = make_float4(1.f, 1.f, 1.f, 1.f), bv = make_float4(0.f, 0.f, 0.f, 0.f);
;   if (rn) gv = *(const float4*)(gain + c);
;   if (bias) bv = *(const float4*)(bias + c);
; #pragma unroll
;   for (int q = 0; q < 8; ++q) {
;     const int row = (tid >> 4) + 16 * q;
;     float4 v = *(const float4*)(Ct + row * 132 + cb + c);
;     v.x += bv.x; v.y += bv.y; v.z += bv.z; v.w += bv.w;
;     if (rn) { const float sc = rn[row * 2 + grp]; v.x *= sc * gv.x; v.y *= sc * gv.y; v.z *= sc * gv.z; v.w *= sc * gv.w; }
;     if (silu) { v.x = siluf(v.x); v.y = siluf(v.y); v.z = siluf(v.z); v.w = siluf(v.w); }
;     uint2 o; o.x = pack2(v.x, v.y); o.y = pack2(v.z, v.w);
;     *(uint2*)(dst + (size_t)(m0 + row) * ldd + dcol0 + c) = o;
;   }
; }
	v_pk_add_f32 v[6:7], v[6:7], 0 op_sel_hi:[1,0]
	s_nop 0
	v_mul_f32_e32 v5, 0xbfb8aa3b, v6
	v_exp_f32_e32 v5, v5
	v_pk_add_f32 v[8:9], v[8:9], 0 op_sel_hi:[1,0]
	v_add_f32_e32 v5, 1.0, v5
	v_rcp_f32_e32 v10, v5
	v_mul_f32_e32 v5, 0xbfb8aa3b, v7
	v_exp_f32_e32 v5, v5
	s_nop 0
	v_add_f32_e32 v5, 1.0, v5
	v_rcp_f32_e32 v11, v5
	v_mul_f32_e32 v5, 0xbfb8aa3b, v8
	v_exp_f32_e32 v5, v5
	v_pk_mul_f32 v[6:7], v[6:7], v[10:11]
	s_nop 0
	v_cvt_pk_bf16_f32 v6, v6, v7
	v_add_f32_e32 v5, 1.0, v5
	v_rcp_f32_e32 v10, v5
	v_mul_f32_e32 v5, 0xbfb8aa3b, v9
	v_exp_f32_e32 v5, v5
	s_nop 0
	v_add_f32_e32 v5, 1.0, v5
	v_rcp_f32_e32 v11, v5
	s_nop 0
	v_pk_mul_f32 v[8:9], v[8:9], v[10:11]
	s_nop 0
	v_cvt_pk_bf16_f32 v7, v8, v9
	v_add_u32_e32 v8, 64, v4
	v_ashrrev_i32_e32 v9, 31, v8
	v_lshlrev_b64 v[8:9], 11, v[8:9]
	v_lshl_add_u64 v[8:9], v[2:3], 0, v[8:9]
	global_store_dwordx2 v[8:9], v[6:7], off
	ds_read_b128 v[6:9], v0 offset:42496
	s_waitcnt lgkmcnt(0)
	v_pk_add_f32 v[6:7], v[6:7], 0 op_sel_hi:[1,0]
	s_nop 0
	v_mul_f32_e32 v5, 0xbfb8aa3b, v6
	v_exp_f32_e32 v5, v5
	v_pk_add_f32 v[8:9], v[8:9], 0 op_sel_hi:[1,0]
	v_add_f32_e32 v5, 1.0, v5
	v_rcp_f32_e32 v10, v5
	v_mul_f32_e32 v5, 0xbfb8aa3b, v7
	v_exp_f32_e32 v5, v5
	s_nop 0
	v_add_f32_e32 v5, 1.0, v5
	v_rcp_f32_e32 v11, v5
	v_mul_f32_e32 v5, 0xbfb8aa3b, v8
	v_exp_f32_e32 v5, v5
	v_pk_mul_f32 v[6:7], v[6:7], v[10:11]
	s_nop 0
	v_cvt_pk_bf16_f32 v6, v6, v7
	v_add_f32_e32 v5, 1.0, v5
	v_rcp_f32_e32 v10, v5
	v_mul_f32_e32 v5, 0xbfb8aa3b, v9
	v_exp_f32_e32 v5, v5
	s_nop 0
	v_add_f32_e32 v5, 1.0, v5
	v_rcp_f32_e32 v11, v5
	s_nop 0
	v_pk_mul_f32 v[8:9], v[8:9], v[10:11]
	s_nop 0
	v_cvt_pk_bf16_f32 v7, v8, v9
	v_add_u32_e32 v8, 0x50, v4
	v_ashrrev_i32_e32 v9, 31, v8
	v_lshlrev_b64 v[8:9], 11, v[8:9]
	v_lshl_add_u64 v[8:9], v[2:3], 0, v[8:9]
	global_store_dwordx2 v[8:9], v[6:7], off
	ds_read_b128 v[6:9], v0 offset:50944
	s_waitcnt lgkmcnt(0)
	v_pk_add_f32 v[6:7], v[6:7], 0 op_sel_hi:[1,0]
	s_nop 0
	v_mul_f32_e32 v5, 0xbfb8aa3b, v6
	v_exp_f32_e32 v5, v5
	v_pk_add_f32 v[8:9], v[8:9], 0 op_sel_hi:[1,0]
	v_add_f32_e32 v5, 1.0, v5
	v_rcp_f32_e32 v10, v5
	v_mul_f32_e32 v5, 0xbfb8aa3b, v7
	v_exp_f32_e32 v5, v5
	s_nop 0
	v_add_f32_e32 v5, 1.0, v5
	v_rcp_f32_e32 v11, v5
	v_mul_f32_e32 v5, 0xbfb8aa3b, v8
	v_exp_f32_e32 v5, v5
	v_pk_mul_f32 v[6:7], v[6:7], v[10:11]
	s_nop 0
	v_cvt_pk_bf16_f32 v6, v6, v7
	v_add_f32_e32 v5, 1.0, v5
	v_rcp_f32_e32 v10, v5
	v_mul_f32_e32 v5, 0xbfb8aa3b, v9
	v_exp_f32_e32 v5, v5
	s_nop 0
	v_add_f32_e32 v5, 1.0, v5
	v_rcp_f32_e32 v11, v5
	s_nop 0
	v_pk_mul_f32 v[8:9], v[8:9], v[10:11]
	s_nop 0
	v_cvt_pk_bf16_f32 v7, v8, v9
	v_add_u32_e32 v8, 0x60, v4
	v_ashrrev_i32_e32 v9, 31, v8
	v_lshlrev_b64 v[8:9], 11, v[8:9]
	v_lshl_add_u64 v[8:9], v[2:3], 0, v[8:9]
	global_store_dwordx2 v[8:9], v[6:7], off
	ds_read_b128 v[6:9], v0 offset:59392
	v_add_u32_e32 v4, 0x70, v4
	v_ashrrev_i32_e32 v5, 31, v4
	v_lshlrev_b64 v[4:5], 11, v[4:5]
	v_lshl_add_u64 v[2:3], v[2:3], 0, v[4:5]
	s_waitcnt lgkmcnt(0)
	v_pk_add_f32 v[6:7], v[6:7], 0 op_sel_hi:[1,0]
	v_pk_add_f32 v[8:9], v[8:9], 0 op_sel_hi:[1,0]
	v_mul_f32_e32 v0, 0xbfb8aa3b, v6
	v_exp_f32_e32 v0, v0
	s_nop 0
	v_add_f32_e32 v0, 1.0, v0
	v_rcp_f32_e32 v10, v0
	v_mul_f32_e32 v0, 0xbfb8aa3b, v7
	v_exp_f32_e32 v0, v0
	s_nop 0
	v_add_f32_e32 v0, 1.0, v0
	v_rcp_f32_e32 v11, v0
	v_mul_f32_e32 v0, 0xbfb8aa3b, v8
	v_exp_f32_e32 v0, v0
	v_pk_mul_f32 v[6:7], v[6:7], v[10:11]
	s_nop 0
	v_cvt_pk_bf16_f32 v6, v6, v7
	v_add_f32_e32 v0, 1.0, v0
	v_rcp_f32_e32 v10, v0
	v_mul_f32_e32 v0, 0xbfb8aa3b, v9
	v_exp_f32_e32 v0, v0
	s_nop 0
	v_add_f32_e32 v0, 1.0, v0
	v_rcp_f32_e32 v11, v0
	s_nop 0
	v_pk_mul_f32 v[8:9], v[8:9], v[10:11]
	s_nop 0
	v_cvt_pk_bf16_f32 v7, v8, v9
	global_store_dwordx2 v[2:3], v[6:7], off

; #define G_STORE(ST, S, unused) do { char* d_ = smem + (ST) * STAGE; \
;     *(uint4*)(d_ + alo[0]) = S##a0; *(uint4*)(d_ + alo[1]) = S##a1; *(uint4*)(d_ + alo[2]) = S##a2; *(uint4*)(d_ + alo[3]) = S##a3; \
;     *(uint4*)(d_ + blo[0]) = S##b0; *(uint4*)(d_ + blo[1]) = S##b1; \
;     if (NBCH == 4) { *(uint4*)(d_ + blo[NBCH - 2]) = S##b2; *(uint4*)(d_ + blo[NBCH - 1]) = S##b3; } } while (0)
; template <int NJ, class RowA>
; DI void gemm_main(f32x16 (&acc)[2][NJ], const bf16_t* __restrict__ A, RowA rowA, size_t kstrideA, int m0, int Mmax,
;                   const bf16_t* __restrict__ Bt, size_t ldb, int n0, int nk, char* smem) {
;     ...
;   __syncthreads();
;   G_LOAD(x0, 0, 0);
;   G_LOAD(x1, 0, 1);
;   G_STORE(0, x0, 0);
;   __syncthreads();
; #pragma unroll 1
;   for (int kt = 0; kt < nk; kt += 2) {
;     G_LOAD(x0, 0, (kt + 2 < nk ? kt + 2 : nk - 1));
;     G_COMPUTE(0);
;     G_STORE(1, x1, 0);
;     __syncthreads();
;     G_LOAD(x1, 0, (kt + 3 < nk ? kt + 3 : nk - 1));
;     G_COMPUTE(1);
;     G_STORE(0, x0, 0);
;     __syncthreads();
;   }
.Lpeel_tail_2149:
	ds_read_b128 v[166:169], v0
	ds_read_b128 v[170:173], v139 offset:18432
	ds_read_b128 v[174:177], v139 offset:23040
	ds_read_b128 v[178:181], v0 offset:4608
	s_add_i32 s1, s0, 4
	s_min_u32 s1, s1, 15
	s_lshl_b32 s14, s1, 7
	v_lshl_add_u64 v[98:99], v[122:123], 0, s[14:15]
	v_lshl_add_u64 v[102:103], v[124:125], 0, s[14:15]
	v_lshl_add_u64 v[106:107], v[126:127], 0, s[14:15]
	v_lshl_add_u64 v[110:111], v[128:129], 0, s[14:15]
	v_lshl_add_u64 v[114:115], v[130:131], 0, s[14:15]
	v_lshl_add_u64 v[118:119], v[132:133], 0, s[14:15]
	s_add_i32 s0, s0, 2
	v_lshl_add_u64 v[158:159], v[134:135], 0, s[14:15]
	v_lshl_add_u64 v[160:161], v[136:137], 0, s[14:15]
	s_setprio 1
	ds_read_b128 v[182:185], v0 offset:32
	ds_read_b128 v[186:189], v139 offset:18464
	ds_read_b128 v[190:193], v139 offset:23072
	ds_read_b128 v[194:197], v0 offset:4640
	s_waitcnt lgkmcnt(4)
	v_mfma_f32_32x32x16_bf16 v[50:65], v[166:169], v[170:173], v[50:65]
	v_mfma_f32_32x32x16_bf16 v[34:49], v[166:169], v[174:177], v[34:49]
	v_mfma_f32_32x32x16_bf16 v[18:33], v[178:181], v[170:173], v[18:33]
	v_mfma_f32_32x32x16_bf16 v[2:17], v[178:181], v[174:177], v[2:17]
	ds_read_b128 v[166:169], v0 offset:64
	ds_read_b128 v[170:173], v139 offset:18496
	ds_read_b128 v[174:177], v139 offset:23104
	ds_read_b128 v[178:181], v0 offset:4672
	s_waitcnt lgkmcnt(4)
	v_mfma_f32_32x32x16_bf16 v[50:65], v[182:185], v[186:189], v[50:65]
	v_mfma_f32_32x32x16_bf16 v[34:49], v[182:185], v[190:193], v[34:49]
	v_mfma_f32_32x32x16_bf16 v[18:33], v[194:197], v[186:189], v[18:33]
	v_mfma_f32_32x32x16_bf16 v[2:17], v[194:197], v[190:193], v[2:17]
	ds_read_b128 v[182:185], v0 offset:96
	ds_read_b128 v[186:189], v139 offset:18528
	ds_read_b128 v[190:193], v139 offset:23136
	ds_read_b128 v[194:197], v0 offset:4704
	s_waitcnt lgkmcnt(4)
	v_mfma_f32_32x32x16_bf16 v[50:65], v[166:169], v[170:173], v[50:65]
	s_waitcnt vmcnt(0)
	ds_write_b128 v138, v[74:77] offset:36864
	v_mfma_f32_32x32x16_bf16 v[34:49], v[166:169], v[174:177], v[34:49]
	ds_write_b128 v140, v[78:81] offset:36864
	v_mfma_f32_32x32x16_bf16 v[18:33], v[178:181], v[170:173], v[18:33]
	ds_write_b128 v142, v[82:85] offset:36864
	v_mfma_f32_32x32x16_bf16 v[2:17], v[178:181], v[174:177], v[2:17]
	ds_write_b128 v144, v[86:89] offset:36864
	s_waitcnt lgkmcnt(4)
	v_mfma_f32_32x32x16_bf16 v[50:65], v[182:185], v[186:189], v[50:65]
	ds_write_b128 v138, v[90:93] offset:55296
	v_mfma_f32_32x32x16_bf16 v[34:49], v[182:185], v[190:193], v[34:49]
	ds_write_b128 v140, v[94:97] offset:55296
	v_mfma_f32_32x32x16_bf16 v[18:33], v[194:197], v[186:189], v[18:33]
	ds_write_b128 v142, v[66:69] offset:55296
	v_mfma_f32_32x32x16_bf16 v[2:17], v[194:197], v[190:193], v[2:17]
	ds_write_b128 v144, v[70:73] offset:55296
	s_setprio 0
	s_min_u32 s1, s0, 12
	s_lshl_b32 s14, s1, 7
	v_lshl_add_u64 v[66:67], v[122:123], 0, s[14:15]
	v_lshl_add_u64 v[68:69], v[124:125], 0, s[14:15]
	v_lshl_add_u64 v[70:71], v[126:127], 0, s[14:15]
	v_lshl_add_u64 v[72:73], v[128:129], 0, s[14:15]
	v_lshl_add_u64 v[90:91], v[130:131], 0, s[14:15]
	v_lshl_add_u64 v[94:95], v[132:133], 0, s[14:15]
	s_waitcnt lgkmcnt(0)
	s_barrier
	ds_read_b128 v[166:169], v0 offset:36864
	ds_read_b128 v[170:173], v139 offset:55296
	ds_read_b128 v[174:177], v139 offset:59904
	ds_read_b128 v[178:181], v0 offset:41472
	v_lshl_add_u64 v[154:155], v[134:135], 0, s[14:15]
	v_lshl_add_u64 v[156:157], v[136:137], 0, s[14:15]
	s_setprio 1
	ds_read_b128 v[182:185], v0 offset:36896
	ds_read_b128 v[186:189], v139 offset:55328
	ds_read_b128 v[190:193], v139 offset:59936
	ds_read_b128 v[194:197], v0 offset:41504
	s_waitcnt lgkmcnt(4)
	v_mfma_f32_32x32x16_bf16 v[50:65], v[166:169], v[170:173], v[50:65]
	s_cmp_lt_u32 s0, 14
	v_mfma_f32_32x32x16_bf16 v[34:49], v[166:169], v[174:177], v[34:49]
	v_mfma_f32_32x32x16_bf16 v[18:33], v[178:181], v[170:173], v[18:33]
	v_mfma_f32_32x32x16_bf16 v[2:17], v[178:181], v[174:177], v[2:17]
	ds_read_b128 v[166:169], v0 offset:36928
	ds_read_b128 v[170:173], v139 offset:55360
	ds_read_b128 v[174:177], v139 offset:59968
	ds_read_b128 v[178:181], v0 offset:41536
	s_waitcnt lgkmcnt(4)
	v_mfma_f32_32x32x16_bf16 v[50:65], v[182:185], v[186:189], v[50:65]
	v_mfma_f32_32x32x16_bf16 v[34:49], v[182:185], v[190:193], v[34:49]
	v_mfma_f32_32x32x16_bf16 v[18:33], v[194:197], v[186:189], v[18:33]
	v_mfma_f32_32x32x16_bf16 v[2:17], v[194:197], v[190:193], v[2:17]
	ds_read_b128 v[182:185], v0 offset:36960
	ds_read_b128 v[186:189], v139 offset:55392
	ds_read_b128 v[190:193], v139 offset:60000
	ds_read_b128 v[194:197], v0 offset:41568
	s_waitcnt lgkmcnt(4)
	v_mfma_f32_32x32x16_bf16 v[50:65], v[166:169], v[170:173], v[50:65]
	v_mfma_f32_32x32x16_bf16 v[34:49], v[166:169], v[174:177], v[34:49]
	v_mfma_f32_32x32x16_bf16 v[18:33], v[178:181], v[170:173], v[18:33]
	v_mfma_f32_32x32x16_bf16 v[2:17], v[178:181], v[174:177], v[2:17]
	s_waitcnt lgkmcnt(0)
	v_mfma_f32_32x32x16_bf16 v[50:65], v[182:185], v[186:189], v[50:65]
	v_mfma_f32_32x32x16_bf16 v[34:49], v[182:185], v[190:193], v[34:49]
	v_mfma_f32_32x32x16_bf16 v[18:33], v[194:197], v[186:189], v[18:33]
	v_mfma_f32_32x32x16_bf16 v[2:17], v[194:197], v[190:193], v[2:17]
	s_setprio 0
	s_waitcnt lgkmcnt(0)
	s_barrier
; #define TIDX (tid_launder())
; DI int crow(int reg, int hh) { return (reg & 3) + 8 * (reg >> 2) + 4 * hh; }
; template <int NJ>
; DI void acc_to_ct(const f32x16 (&acc)[2][NJ], float* Ct) {
;   const int lane = TIDX & 63, wid = TIDX >> 6, wm = wid >> 1, wn = wid & 1;
;   const int r = lane & 31, hh = lane >> 5;
; #pragma unroll
;   for (int i = 0; i < 2; ++i)
; #pragma unroll
;     for (int j = 0; j < NJ; ++j)
; #pragma unroll
;       for (int e = 0; e < 16; ++e) Ct[(wm * 64 + i * 32 + crow(e, hh)) * 132 + wn * 32 * NJ + j * 32 + r] = acc[i][j][e];
;   __syncthreads();
; DI void epi_storeVF(const float* Ct, int cb, bf16_t* dst) {
;   for (int idx = TIDX; idx < 1024; idx += 256) {
;     const int kt4 = idx >> 8, slot = idx & 255, r = slot & 31, hh = (slot >> 5) & 1, s2 = (slot >> 6) & 1, dt = slot >> 7;
;     float v[8];
	v_mov_b32_e32 v0, v230
	s_waitcnt vmcnt(1)
	v_mov_b32_e32 v66, v230
	v_and_b32_e32 v67, 31, v0
	v_lshrrev_b32_e32 v0, 3, v0
	v_and_b32_e32 v0, 4, v0
	v_lshrrev_b32_e32 v68, 1, v66
	v_and_or_b32 v0, v68, s47, v0
	v_and_or_b32 v66, v66, 64, v67
	v_mul_lo_u32 v0, v0, s79
	v_lshl_add_u32 v0, v66, 2, v0
	ds_write2_b32 v0, v50, v34 offset1:32
	ds_write2_b32 v0, v51, v35 offset0:132 offset1:164
	v_add_u32_e32 v34, 0x400, v0
	ds_write2_b32 v34, v52, v36 offset0:8 offset1:40
	ds_write2_b32 v34, v53, v37 offset0:140 offset1:172
	v_add_u32_e32 v34, 0x1000, v0
	ds_write2_b32 v34, v54, v38 offset0:32 offset1:64
	ds_write2_b32 v34, v55, v39 offset0:164 offset1:196
	v_add_u32_e32 v34, 0x1400, v0
	ds_write2_b32 v34, v56, v40 offset0:40 offset1:72
	ds_write2_b32 v34, v57, v41 offset0:172 offset1:204
	v_add_u32_e32 v34, 0x2000, v0
	ds_write2_b32 v34, v58, v42 offset0:64 offset1:96
	ds_write2_b32 v34, v59, v43 offset0:196 offset1:228
	v_add_u32_e32 v34, 0x2400, v0
	ds_write2_b32 v34, v60, v44 offset0:72 offset1:104
	ds_write2_b32 v34, v61, v45 offset0:204 offset1:236
	v_add_u32_e32 v34, 0x3000, v0
	ds_write2_b32 v34, v62, v46 offset0:96 offset1:128
	v_add_u32_e32 v34, 0x3200, v0
	ds_write2_b32 v34, v63, v47 offset0:100 offset1:132
	v_add_u32_e32 v34, 0x3400, v0
	ds_write2_b32 v34, v64, v48 offset0:104 offset1:136
	v_add_u32_e32 v34, 0x3600, v0
	ds_write2_b32 v34, v65, v49 offset0:108 offset1:140
	v_add_u32_e32 v34, 0x4000, v0
	ds_write2_b32 v34, v18, v2 offset0:128 offset1:160
	v_add_u32_e32 v2, 0x4400, v0
	ds_write2_b32 v2, v19, v3 offset0:4 offset1:36
	ds_write2_b32 v2, v20, v4 offset0:136 offset1:168
	v_add_u32_e32 v2, 0x4800, v0
	ds_write2_b32 v2, v21, v5 offset0:12 offset1:44
	v_add_u32_e32 v2, 0x5000, v0
	ds_write2_b32 v2, v22, v6 offset0:160 offset1:192
	v_add_u32_e32 v2, 0x5400, v0
	ds_write2_b32 v2, v23, v7 offset0:36 offset1:68
	ds_write2_b32 v2, v24, v8 offset0:168 offset1:200
	v_add_u32_e32 v2, 0x5800, v0
	ds_write2_b32 v2, v25, v9 offset0:44 offset1:76
	v_add_u32_e32 v2, 0x6000, v0
	ds_write2_b32 v2, v26, v10 offset0:192 offset1:224
	v_add_u32_e32 v2, 0x6400, v0
	ds_write2_b32 v2, v27, v11 offset0:68 offset1:100
	ds_write2_b32 v2, v28, v12 offset0:200 offset1:232
	v_add_u32_e32 v2, 0x6800, v0
	ds_write2_b32 v2, v29, v13 offset0:76 offset1:108
	v_add_u32_e32 v2, 0x7200, v0
	ds_write2_b32 v2, v30, v14 offset0:96 offset1:128
	v_add_u32_e32 v2, 0x7400, v0
	ds_write2_b32 v2, v31, v15 offset0:100 offset1:132
	v_add_u32_e32 v2, 0x7600, v0
	v_add_u32_e32 v0, 0x7800, v0
	s_cmp_gt_u32 s35, 3
	s_mov_b64 s[0:1], -1
	ds_write2_b32 v2, v32, v16 offset0:104 offset1:136
	ds_write2_b32 v0, v33, v17 offset0:108 offset1:140
	s_waitcnt lgkmcnt(0)
	s_barrier
	s_cbranch_scc0 .LBB0_2277
	s_cmp_lg_u32 s35, 4
	s_cbranch_scc0 .LBB0_2236
	s_cmp_gt_u32 s35, 8
	s_cbranch_scc0 .LBB0_2233
	s_ashr_i32 s0, s2, 6
	s_add_i32 s2, s0, s3
	s_ashr_i32 s0, s13, 31
	s_lshr_b32 s0, s0, 21
	s_add_i32 s0, s13, s0
	s_and_b32 s0, s0, 0xfffff800
	s_sub_i32 s14, s13, s0
	s_mov_b64 s[0:1], -1
	s_mov_b64 s[6:7], 0
	s_cmp_lt_i32 s68, -1
	s_mov_b64 s[4:5], 0
	s_cbranch_scc1 .LBB0_2199
	s_cmp_gt_i32 s68, -1
	s_cbranch_scc0 .LBB0_2169
	s_cmp_eq_u32 s68, 0
	s_mov_b64 s[4:5], -1
	s_cbranch_scc0 .LBB0_2168
	v_mov_b32_e32 v2, v230
	s_movk_i32 s0, 0x400
	s_nop 0
	v_cmp_gt_i32_e32 vcc, s0, v2
	s_and_saveexec_b64 s[0:1], vcc
	s_movk_i32 s36, 0x2ff
	s_cbranch_execz .LBB0_2159
	s_ashr_i32 s3, s2, 31
	s_ashr_i32 s4, s14, 5
	v_readlane_b32 s16, v250, 34
	s_ashr_i32 s5, s4, 31
	s_lshl_b64 s[8:9], s[2:3], 18
	v_readlane_b32 s22, v250, 40
	v_readlane_b32 s23, v250, 41
	s_add_u32 s3, s22, s8
	s_addc_u32 s8, s23, s9
	s_lshl_b64 s[4:5], s[4:5], 12
	s_add_u32 s4, s3, s4
	v_and_b32_e32 v0, 31, v2
	s_addc_u32 s5, s8, s5
	v_lshlrev_b32_e32 v3, 2, v0
	v_lshlrev_b32_e32 v4, 3, v2
	s_mov_b64 s[8:9], 0
	v_readlane_b32 s17, v250, 35
	v_readlane_b32 s18, v250, 36
	v_readlane_b32 s19, v250, 37
	v_readlane_b32 s20, v250, 38
	v_readlane_b32 s21, v250, 39
	v_readlane_b32 s24, v250, 42
	v_readlane_b32 s25, v250, 43
	v_readlane_b32 s26, v250, 44
	v_readlane_b32 s27, v250, 45
	v_readlane_b32 s28, v250, 46
	v_readlane_b32 s29, v250, 47
	v_readlane_b32 s30, v250, 48
	v_readlane_b32 s31, v250, 49
